# scan phase rewritten by hand: staging waves with 8-byte loads prefetched two chunks ahead, LDS layout with kk/r interleaved so both dot products run in one packed chain, v read 4 steps at a time
# speedup vs baseline: 1.0037x; 1.0037x over previous
.LBB0_41:
	s_andn2_b64 vcc, exec, s[6:7]
	s_cbranch_vccnz .LBB0_61
	v_readlane_b32 s4, v242, 4
	v_readlane_b32 s5, v242, 5
	v_mov_b32_e32 v8, v173
	s_andn2_b64 vcc, exec, s[4:5]
	s_cbranch_vccnz .LBB0_61
	v_lshrrev_b32_e32 v0, 6, v173
	s_mov_b32 s4, s2
	s_nop 3
	v_readfirstlane_b32 s7, v0
.Lsc_item:
	s_cmp_ge_u32 s7, 4
	s_cbranch_scc1 .Lsc_G
	v_lshlrev_b32_e32 v27, 2, v173
	v_and_b32_e32 v27, 60, v27
	v_lshlrev_b32_e32 v7, 2, v0
	v_bfe_u32 v1, v173, 4, 2
	v_or_b32_e32 v37, v7, v1
	v_lshlrev_b32_e32 v37, 5, v37
	v_and_b32_e32 v36, 7, v173
	v_lshl_add_u32 v37, v36, 2, v37
	v_add_u32_e32 v37, 89088, v37
	v_and_b32_e32 v34, 15, v173
	v_lshlrev_b32_e32 v34, 4, v34
	v_or_b32_e32 v35, v7, v1
	v_mul_u32_u24_e32 v35, 144, v35
	v_add_u32_e32 v35, 84480, v35
	v_mov_b32_e32 v8, 0
	v_mov_b32_e32 v9, 0
	v_mov_b32_e32 v10, 0
	v_mov_b32_e32 v11, 0
	s_mov_b32 s6, 0
	s_mov_b32 s5, 0
.Lsc_S_loop:
	s_cmp_eq_u32 s6, 0
	s_cbranch_scc1 .Lsc_S_sync
	s_cmp_gt_u32 s6, 0x100
	s_cbranch_scc1 .Lsc_S_sync
	s_bitcmp0_b32 s5, 5
	s_cselect_b32 s54, 1, 0
	s_mul_i32 s55, s54, 42240
	v_add_u32_e32 v13, s55, v34
	s_mul_i32 s55, s54, 2304
	v_add_u32_e32 v14, s55, v35
	v_lshl_add_u32 v12, s54, 14, v37
	ds_read_b128 v[40:43], v13 offset:41728
	ds_read_b128 v[44:47], v13 offset:41984
	ds_read_b128 v[156:159], v14 offset:0
	ds_read_b128 v[76:79], v13 offset:0
	ds_read_b128 v[80:83], v13 offset:256
	ds_read_b128 v[84:87], v13 offset:512
	ds_read_b128 v[88:91], v13 offset:768
	ds_read_b128 v[92:95], v13 offset:1024
	ds_read_b128 v[96:99], v13 offset:1280
	ds_read_b128 v[100:103], v13 offset:1536
	ds_read_b128 v[104:107], v13 offset:1792
	ds_read_b128 v[108:111], v13 offset:2048
	ds_read_b128 v[112:115], v13 offset:2304
	s_waitcnt lgkmcnt(12)
	v_mul_f32_e32 v24, v10, v40
	v_fmac_f32_e32 v24, v11, v42
	s_waitcnt lgkmcnt(11)
	v_fmac_f32_e32 v24, v8, v44
	v_fmac_f32_e32 v24, v9, v46
	s_waitcnt lgkmcnt(8)
	v_pk_mul_f32 v[20:21], v[80:81], v[156:157] op_sel_hi:[1,0]
	v_pk_mul_f32 v[22:23], v[82:83], v[156:157] op_sel_hi:[1,0]
	v_add_f32_dpp v15, v24, v24 row_ror:8 row_mask:0xf bank_mask:0xf bound_ctrl:1
	v_pk_fma_f32 v[16:17], v[10:11], v[76:77], v[20:21]
	v_pk_fma_f32 v[18:19], v[8:9], v[78:79], v[22:23]
	v_add_f32_dpp v15, v15, v15 row_ror:4 row_mask:0xf bank_mask:0xf bound_ctrl:1
	ds_read_b128 v[116:119], v13 offset:2560
	ds_read_b128 v[120:123], v13 offset:2816
	v_add_f32_dpp v15, v15, v15 row_ror:2 row_mask:0xf bank_mask:0xf bound_ctrl:1
	ds_read_b128 v[124:127], v13 offset:3072
	ds_read_b128 v[128:131], v13 offset:3328
	v_add_f32_dpp v30, v15, v15 row_ror:1 row_mask:0xf bank_mask:0xf bound_ctrl:1
	ds_read_b128 v[132:135], v13 offset:3584
	s_waitcnt lgkmcnt(12)
	v_pk_fma_f32 v[10:11], v[84:85], v[30:31], v[16:17] op_sel_hi:[1,0,1] neg_lo:[0,1,0] neg_hi:[0,1,0]
	v_pk_fma_f32 v[8:9], v[86:87], v[30:31], v[18:19] op_sel_hi:[1,0,1] neg_lo:[0,1,0] neg_hi:[0,1,0]
	s_waitcnt lgkmcnt(11)
	v_pk_mul_f32 v[24:25], v[10:11], v[88:89] op_sel:[0,0] op_sel_hi:[0,1]
	v_pk_fma_f32 v[24:25], v[10:11], v[90:91], v[24:25] op_sel:[1,0,0] op_sel_hi:[1,1,1]
	s_waitcnt lgkmcnt(10)
	v_pk_fma_f32 v[24:25], v[8:9], v[92:93], v[24:25] op_sel:[0,0,0] op_sel_hi:[0,1,1]
	v_pk_fma_f32 v[24:25], v[8:9], v[94:95], v[24:25] op_sel:[1,0,0] op_sel_hi:[1,1,1]
	s_waitcnt lgkmcnt(8)
	v_pk_mul_f32 v[20:21], v[100:101], v[156:157] op_sel:[0,1] op_sel_hi:[1,1]
	v_pk_mul_f32 v[22:23], v[102:103], v[156:157] op_sel:[0,1] op_sel_hi:[1,1]
	v_add_f32_dpp v15, v24, v24 row_ror:8 row_mask:0xf bank_mask:0xf bound_ctrl:1
	v_pk_fma_f32 v[16:17], v[10:11], v[96:97], v[20:21]
	v_pk_fma_f32 v[18:19], v[8:9], v[98:99], v[22:23]
	v_add_f32_dpp v15, v15, v15 row_ror:4 row_mask:0xf bank_mask:0xf bound_ctrl:1
	v_add_f32_dpp v32, v25, v25 row_ror:8 row_mask:0xf bank_mask:0xf bound_ctrl:1
	ds_read_b128 v[136:139], v13 offset:3840
	v_add_f32_dpp v15, v15, v15 row_ror:2 row_mask:0xf bank_mask:0xf bound_ctrl:1
	ds_read_b128 v[140:143], v13 offset:4096
	ds_read_b128 v[144:147], v13 offset:4352
	v_add_f32_dpp v30, v15, v15 row_ror:1 row_mask:0xf bank_mask:0xf bound_ctrl:1
	ds_read_b128 v[148:151], v13 offset:4608
	ds_read_b128 v[152:155], v13 offset:4864
	ds_read_b128 v[160:163], v14 offset:16
	s_waitcnt lgkmcnt(13)
	v_pk_fma_f32 v[10:11], v[104:105], v[30:31], v[16:17] op_sel_hi:[1,0,1] neg_lo:[0,1,0] neg_hi:[0,1,0]
	v_pk_fma_f32 v[8:9], v[106:107], v[30:31], v[18:19] op_sel_hi:[1,0,1] neg_lo:[0,1,0] neg_hi:[0,1,0]
	s_waitcnt lgkmcnt(12)
	v_pk_mul_f32 v[24:25], v[10:11], v[108:109] op_sel:[0,0] op_sel_hi:[0,1]
	v_pk_fma_f32 v[24:25], v[10:11], v[110:111], v[24:25] op_sel:[1,0,0] op_sel_hi:[1,1,1]
	s_waitcnt lgkmcnt(11)
	v_pk_fma_f32 v[24:25], v[8:9], v[112:113], v[24:25] op_sel:[0,0,0] op_sel_hi:[0,1,1]
	v_pk_fma_f32 v[24:25], v[8:9], v[114:115], v[24:25] op_sel:[1,0,0] op_sel_hi:[1,1,1]
	s_waitcnt lgkmcnt(9)
	v_pk_mul_f32 v[20:21], v[120:121], v[158:159] op_sel_hi:[1,0]
	v_pk_mul_f32 v[22:23], v[122:123], v[158:159] op_sel_hi:[1,0]
	v_add_f32_dpp v15, v24, v24 row_ror:8 row_mask:0xf bank_mask:0xf bound_ctrl:1
	v_pk_fma_f32 v[16:17], v[10:11], v[116:117], v[20:21]
	v_pk_fma_f32 v[18:19], v[8:9], v[118:119], v[22:23]
	v_add_f32_dpp v15, v15, v15 row_ror:4 row_mask:0xf bank_mask:0xf bound_ctrl:1
	v_add_f32_dpp v33, v25, v25 row_ror:8 row_mask:0xf bank_mask:0xf bound_ctrl:1
	ds_read_b128 v[76:79], v13 offset:5120
	v_add_f32_dpp v15, v15, v15 row_ror:2 row_mask:0xf bank_mask:0xf bound_ctrl:1
	ds_read_b128 v[80:83], v13 offset:5376
	ds_read_b128 v[84:87], v13 offset:5632
	v_add_f32_dpp v30, v15, v15 row_ror:1 row_mask:0xf bank_mask:0xf bound_ctrl:1
	ds_read_b128 v[88:91], v13 offset:5888
	ds_read_b128 v[92:95], v13 offset:6144
	ds_write2st64_b32 v12, v32, v33 offset0:0 offset1:2
	s_waitcnt lgkmcnt(6)
	v_pk_fma_f32 v[10:11], v[124:125], v[30:31], v[16:17] op_sel_hi:[1,0,1] neg_lo:[0,1,0] neg_hi:[0,1,0]
	v_pk_fma_f32 v[8:9], v[126:127], v[30:31], v[18:19] op_sel_hi:[1,0,1] neg_lo:[0,1,0] neg_hi:[0,1,0]
	v_pk_mul_f32 v[24:25], v[10:11], v[128:129] op_sel:[0,0] op_sel_hi:[0,1]
	v_pk_fma_f32 v[24:25], v[10:11], v[130:131], v[24:25] op_sel:[1,0,0] op_sel_hi:[1,1,1]
	v_pk_fma_f32 v[24:25], v[8:9], v[132:133], v[24:25] op_sel:[0,0,0] op_sel_hi:[0,1,1]
	v_pk_fma_f32 v[24:25], v[8:9], v[134:135], v[24:25] op_sel:[1,0,0] op_sel_hi:[1,1,1]
	v_pk_mul_f32 v[20:21], v[140:141], v[158:159] op_sel:[0,1] op_sel_hi:[1,1]
	v_pk_mul_f32 v[22:23], v[142:143], v[158:159] op_sel:[0,1] op_sel_hi:[1,1]
	v_add_f32_dpp v15, v24, v24 row_ror:8 row_mask:0xf bank_mask:0xf bound_ctrl:1
	v_pk_fma_f32 v[16:17], v[10:11], v[136:137], v[20:21]
	v_pk_fma_f32 v[18:19], v[8:9], v[138:139], v[22:23]
	v_add_f32_dpp v15, v15, v15 row_ror:4 row_mask:0xf bank_mask:0xf bound_ctrl:1
	v_add_f32_dpp v32, v25, v25 row_ror:8 row_mask:0xf bank_mask:0xf bound_ctrl:1
	ds_read_b128 v[96:99], v13 offset:6400
	v_add_f32_dpp v15, v15, v15 row_ror:2 row_mask:0xf bank_mask:0xf bound_ctrl:1
	ds_read_b128 v[100:103], v13 offset:6656
	ds_read_b128 v[104:107], v13 offset:6912
	v_add_f32_dpp v30, v15, v15 row_ror:1 row_mask:0xf bank_mask:0xf bound_ctrl:1
	ds_read_b128 v[108:111], v13 offset:7168
	ds_read_b128 v[112:115], v13 offset:7424
	s_waitcnt lgkmcnt(5)
	v_pk_fma_f32 v[10:11], v[144:145], v[30:31], v[16:17] op_sel_hi:[1,0,1] neg_lo:[0,1,0] neg_hi:[0,1,0]
	v_pk_fma_f32 v[8:9], v[146:147], v[30:31], v[18:19] op_sel_hi:[1,0,1] neg_lo:[0,1,0] neg_hi:[0,1,0]
	v_pk_mul_f32 v[24:25], v[10:11], v[148:149] op_sel:[0,0] op_sel_hi:[0,1]
	v_pk_fma_f32 v[24:25], v[10:11], v[150:151], v[24:25] op_sel:[1,0,0] op_sel_hi:[1,1,1]
	v_pk_fma_f32 v[24:25], v[8:9], v[152:153], v[24:25] op_sel:[0,0,0] op_sel_hi:[0,1,1]
	v_pk_fma_f32 v[24:25], v[8:9], v[154:155], v[24:25] op_sel:[1,0,0] op_sel_hi:[1,1,1]
	v_pk_mul_f32 v[20:21], v[80:81], v[160:161] op_sel_hi:[1,0]
	v_pk_mul_f32 v[22:23], v[82:83], v[160:161] op_sel_hi:[1,0]
	v_add_f32_dpp v15, v24, v24 row_ror:8 row_mask:0xf bank_mask:0xf bound_ctrl:1
	v_pk_fma_f32 v[16:17], v[10:11], v[76:77], v[20:21]
	v_pk_fma_f32 v[18:19], v[8:9], v[78:79], v[22:23]
	v_add_f32_dpp v15, v15, v15 row_ror:4 row_mask:0xf bank_mask:0xf bound_ctrl:1
	v_add_f32_dpp v33, v25, v25 row_ror:8 row_mask:0xf bank_mask:0xf bound_ctrl:1
	ds_read_b128 v[116:119], v13 offset:7680
	v_add_f32_dpp v15, v15, v15 row_ror:2 row_mask:0xf bank_mask:0xf bound_ctrl:1
	ds_read_b128 v[120:123], v13 offset:7936
	ds_read_b128 v[124:127], v13 offset:8192
	v_add_f32_dpp v30, v15, v15 row_ror:1 row_mask:0xf bank_mask:0xf bound_ctrl:1
	ds_read_b128 v[128:131], v13 offset:8448
	ds_read_b128 v[132:135], v13 offset:8704
	ds_write2st64_b32 v12, v32, v33 offset0:4 offset1:6
	s_waitcnt lgkmcnt(6)
	v_pk_fma_f32 v[10:11], v[84:85], v[30:31], v[16:17] op_sel_hi:[1,0,1] neg_lo:[0,1,0] neg_hi:[0,1,0]
	v_pk_fma_f32 v[8:9], v[86:87], v[30:31], v[18:19] op_sel_hi:[1,0,1] neg_lo:[0,1,0] neg_hi:[0,1,0]
	v_pk_mul_f32 v[24:25], v[10:11], v[88:89] op_sel:[0,0] op_sel_hi:[0,1]
	v_pk_fma_f32 v[24:25], v[10:11], v[90:91], v[24:25] op_sel:[1,0,0] op_sel_hi:[1,1,1]
	v_pk_fma_f32 v[24:25], v[8:9], v[92:93], v[24:25] op_sel:[0,0,0] op_sel_hi:[0,1,1]
	v_pk_fma_f32 v[24:25], v[8:9], v[94:95], v[24:25] op_sel:[1,0,0] op_sel_hi:[1,1,1]
	v_pk_mul_f32 v[20:21], v[100:101], v[160:161] op_sel:[0,1] op_sel_hi:[1,1]
	v_pk_mul_f32 v[22:23], v[102:103], v[160:161] op_sel:[0,1] op_sel_hi:[1,1]
	v_add_f32_dpp v15, v24, v24 row_ror:8 row_mask:0xf bank_mask:0xf bound_ctrl:1
	v_pk_fma_f32 v[16:17], v[10:11], v[96:97], v[20:21]
	v_pk_fma_f32 v[18:19], v[8:9], v[98:99], v[22:23]
	v_add_f32_dpp v15, v15, v15 row_ror:4 row_mask:0xf bank_mask:0xf bound_ctrl:1
	v_add_f32_dpp v32, v25, v25 row_ror:8 row_mask:0xf bank_mask:0xf bound_ctrl:1
	ds_read_b128 v[136:139], v13 offset:8960
	v_add_f32_dpp v15, v15, v15 row_ror:2 row_mask:0xf bank_mask:0xf bound_ctrl:1
	ds_read_b128 v[140:143], v13 offset:9216
	ds_read_b128 v[144:147], v13 offset:9472
	v_add_f32_dpp v30, v15, v15 row_ror:1 row_mask:0xf bank_mask:0xf bound_ctrl:1
	ds_read_b128 v[148:151], v13 offset:9728
	ds_read_b128 v[152:155], v13 offset:9984
	ds_read_b128 v[156:159], v14 offset:32
	s_waitcnt lgkmcnt(6)
	v_pk_fma_f32 v[10:11], v[104:105], v[30:31], v[16:17] op_sel_hi:[1,0,1] neg_lo:[0,1,0] neg_hi:[0,1,0]
	v_pk_fma_f32 v[8:9], v[106:107], v[30:31], v[18:19] op_sel_hi:[1,0,1] neg_lo:[0,1,0] neg_hi:[0,1,0]
	v_pk_mul_f32 v[24:25], v[10:11], v[108:109] op_sel:[0,0] op_sel_hi:[0,1]
	v_pk_fma_f32 v[24:25], v[10:11], v[110:111], v[24:25] op_sel:[1,0,0] op_sel_hi:[1,1,1]
	v_pk_fma_f32 v[24:25], v[8:9], v[112:113], v[24:25] op_sel:[0,0,0] op_sel_hi:[0,1,1]
	v_pk_fma_f32 v[24:25], v[8:9], v[114:115], v[24:25] op_sel:[1,0,0] op_sel_hi:[1,1,1]
	v_pk_mul_f32 v[20:21], v[120:121], v[162:163] op_sel_hi:[1,0]
	v_pk_mul_f32 v[22:23], v[122:123], v[162:163] op_sel_hi:[1,0]
	v_add_f32_dpp v15, v24, v24 row_ror:8 row_mask:0xf bank_mask:0xf bound_ctrl:1
	v_pk_fma_f32 v[16:17], v[10:11], v[116:117], v[20:21]
	v_pk_fma_f32 v[18:19], v[8:9], v[118:119], v[22:23]
	v_add_f32_dpp v15, v15, v15 row_ror:4 row_mask:0xf bank_mask:0xf bound_ctrl:1
	v_add_f32_dpp v33, v25, v25 row_ror:8 row_mask:0xf bank_mask:0xf bound_ctrl:1
	ds_read_b128 v[76:79], v13 offset:10240
	v_add_f32_dpp v15, v15, v15 row_ror:2 row_mask:0xf bank_mask:0xf bound_ctrl:1
	ds_read_b128 v[80:83], v13 offset:10496
	ds_read_b128 v[84:87], v13 offset:10752
	v_add_f32_dpp v30, v15, v15 row_ror:1 row_mask:0xf bank_mask:0xf bound_ctrl:1
	ds_read_b128 v[88:91], v13 offset:11008
	ds_read_b128 v[92:95], v13 offset:11264
	ds_write2st64_b32 v12, v32, v33 offset0:8 offset1:10
	s_waitcnt lgkmcnt(6)
	v_pk_fma_f32 v[10:11], v[124:125], v[30:31], v[16:17] op_sel_hi:[1,0,1] neg_lo:[0,1,0] neg_hi:[0,1,0]
	v_pk_fma_f32 v[8:9], v[126:127], v[30:31], v[18:19] op_sel_hi:[1,0,1] neg_lo:[0,1,0] neg_hi:[0,1,0]
	v_pk_mul_f32 v[24:25], v[10:11], v[128:129] op_sel:[0,0] op_sel_hi:[0,1]
	v_pk_fma_f32 v[24:25], v[10:11], v[130:131], v[24:25] op_sel:[1,0,0] op_sel_hi:[1,1,1]
	v_pk_fma_f32 v[24:25], v[8:9], v[132:133], v[24:25] op_sel:[0,0,0] op_sel_hi:[0,1,1]
	v_pk_fma_f32 v[24:25], v[8:9], v[134:135], v[24:25] op_sel:[1,0,0] op_sel_hi:[1,1,1]
	v_pk_mul_f32 v[20:21], v[140:141], v[162:163] op_sel:[0,1] op_sel_hi:[1,1]
	v_pk_mul_f32 v[22:23], v[142:143], v[162:163] op_sel:[0,1] op_sel_hi:[1,1]
	v_add_f32_dpp v15, v24, v24 row_ror:8 row_mask:0xf bank_mask:0xf bound_ctrl:1
	v_pk_fma_f32 v[16:17], v[10:11], v[136:137], v[20:21]
	v_pk_fma_f32 v[18:19], v[8:9], v[138:139], v[22:23]
	v_add_f32_dpp v15, v15, v15 row_ror:4 row_mask:0xf bank_mask:0xf bound_ctrl:1
	v_add_f32_dpp v32, v25, v25 row_ror:8 row_mask:0xf bank_mask:0xf bound_ctrl:1
	ds_read_b128 v[96:99], v13 offset:11520
	v_add_f32_dpp v15, v15, v15 row_ror:2 row_mask:0xf bank_mask:0xf bound_ctrl:1
	ds_read_b128 v[100:103], v13 offset:11776
	ds_read_b128 v[104:107], v13 offset:12032
	v_add_f32_dpp v30, v15, v15 row_ror:1 row_mask:0xf bank_mask:0xf bound_ctrl:1
	ds_read_b128 v[108:111], v13 offset:12288
	ds_read_b128 v[112:115], v13 offset:12544
	s_waitcnt lgkmcnt(5)
	v_pk_fma_f32 v[10:11], v[144:145], v[30:31], v[16:17] op_sel_hi:[1,0,1] neg_lo:[0,1,0] neg_hi:[0,1,0]
	v_pk_fma_f32 v[8:9], v[146:147], v[30:31], v[18:19] op_sel_hi:[1,0,1] neg_lo:[0,1,0] neg_hi:[0,1,0]
	v_pk_mul_f32 v[24:25], v[10:11], v[148:149] op_sel:[0,0] op_sel_hi:[0,1]
	v_pk_fma_f32 v[24:25], v[10:11], v[150:151], v[24:25] op_sel:[1,0,0] op_sel_hi:[1,1,1]
	v_pk_fma_f32 v[24:25], v[8:9], v[152:153], v[24:25] op_sel:[0,0,0] op_sel_hi:[0,1,1]
	v_pk_fma_f32 v[24:25], v[8:9], v[154:155], v[24:25] op_sel:[1,0,0] op_sel_hi:[1,1,1]
	v_pk_mul_f32 v[20:21], v[80:81], v[156:157] op_sel_hi:[1,0]
	v_pk_mul_f32 v[22:23], v[82:83], v[156:157] op_sel_hi:[1,0]
	v_add_f32_dpp v15, v24, v24 row_ror:8 row_mask:0xf bank_mask:0xf bound_ctrl:1
	v_pk_fma_f32 v[16:17], v[10:11], v[76:77], v[20:21]
	v_pk_fma_f32 v[18:19], v[8:9], v[78:79], v[22:23]
	v_add_f32_dpp v15, v15, v15 row_ror:4 row_mask:0xf bank_mask:0xf bound_ctrl:1
	v_add_f32_dpp v33, v25, v25 row_ror:8 row_mask:0xf bank_mask:0xf bound_ctrl:1
	ds_read_b128 v[116:119], v13 offset:12800
	v_add_f32_dpp v15, v15, v15 row_ror:2 row_mask:0xf bank_mask:0xf bound_ctrl:1
	ds_read_b128 v[120:123], v13 offset:13056
	ds_read_b128 v[124:127], v13 offset:13312
	v_add_f32_dpp v30, v15, v15 row_ror:1 row_mask:0xf bank_mask:0xf bound_ctrl:1
	ds_read_b128 v[128:131], v13 offset:13568
	ds_read_b128 v[132:135], v13 offset:13824
	ds_write2st64_b32 v12, v32, v33 offset0:12 offset1:14
	s_waitcnt lgkmcnt(6)
	v_pk_fma_f32 v[10:11], v[84:85], v[30:31], v[16:17] op_sel_hi:[1,0,1] neg_lo:[0,1,0] neg_hi:[0,1,0]
	v_pk_fma_f32 v[8:9], v[86:87], v[30:31], v[18:19] op_sel_hi:[1,0,1] neg_lo:[0,1,0] neg_hi:[0,1,0]
	v_pk_mul_f32 v[24:25], v[10:11], v[88:89] op_sel:[0,0] op_sel_hi:[0,1]
	v_pk_fma_f32 v[24:25], v[10:11], v[90:91], v[24:25] op_sel:[1,0,0] op_sel_hi:[1,1,1]
	v_pk_fma_f32 v[24:25], v[8:9], v[92:93], v[24:25] op_sel:[0,0,0] op_sel_hi:[0,1,1]
	v_pk_fma_f32 v[24:25], v[8:9], v[94:95], v[24:25] op_sel:[1,0,0] op_sel_hi:[1,1,1]
	v_pk_mul_f32 v[20:21], v[100:101], v[156:157] op_sel:[0,1] op_sel_hi:[1,1]
	v_pk_mul_f32 v[22:23], v[102:103], v[156:157] op_sel:[0,1] op_sel_hi:[1,1]
	v_add_f32_dpp v15, v24, v24 row_ror:8 row_mask:0xf bank_mask:0xf bound_ctrl:1
	v_pk_fma_f32 v[16:17], v[10:11], v[96:97], v[20:21]
	v_pk_fma_f32 v[18:19], v[8:9], v[98:99], v[22:23]
	v_add_f32_dpp v15, v15, v15 row_ror:4 row_mask:0xf bank_mask:0xf bound_ctrl:1
	v_add_f32_dpp v32, v25, v25 row_ror:8 row_mask:0xf bank_mask:0xf bound_ctrl:1
	ds_read_b128 v[136:139], v13 offset:14080
	v_add_f32_dpp v15, v15, v15 row_ror:2 row_mask:0xf bank_mask:0xf bound_ctrl:1
	ds_read_b128 v[140:143], v13 offset:14336
	ds_read_b128 v[144:147], v13 offset:14592
	v_add_f32_dpp v30, v15, v15 row_ror:1 row_mask:0xf bank_mask:0xf bound_ctrl:1
	ds_read_b128 v[148:151], v13 offset:14848
	ds_read_b128 v[152:155], v13 offset:15104
	ds_read_b128 v[160:163], v14 offset:48
	s_waitcnt lgkmcnt(6)
	v_pk_fma_f32 v[10:11], v[104:105], v[30:31], v[16:17] op_sel_hi:[1,0,1] neg_lo:[0,1,0] neg_hi:[0,1,0]
	v_pk_fma_f32 v[8:9], v[106:107], v[30:31], v[18:19] op_sel_hi:[1,0,1] neg_lo:[0,1,0] neg_hi:[0,1,0]
	v_pk_mul_f32 v[24:25], v[10:11], v[108:109] op_sel:[0,0] op_sel_hi:[0,1]
	v_pk_fma_f32 v[24:25], v[10:11], v[110:111], v[24:25] op_sel:[1,0,0] op_sel_hi:[1,1,1]
	v_pk_fma_f32 v[24:25], v[8:9], v[112:113], v[24:25] op_sel:[0,0,0] op_sel_hi:[0,1,1]
	v_pk_fma_f32 v[24:25], v[8:9], v[114:115], v[24:25] op_sel:[1,0,0] op_sel_hi:[1,1,1]
	v_pk_mul_f32 v[20:21], v[120:121], v[158:159] op_sel_hi:[1,0]
	v_pk_mul_f32 v[22:23], v[122:123], v[158:159] op_sel_hi:[1,0]
	v_add_f32_dpp v15, v24, v24 row_ror:8 row_mask:0xf bank_mask:0xf bound_ctrl:1
	v_pk_fma_f32 v[16:17], v[10:11], v[116:117], v[20:21]
	v_pk_fma_f32 v[18:19], v[8:9], v[118:119], v[22:23]
	v_add_f32_dpp v15, v15, v15 row_ror:4 row_mask:0xf bank_mask:0xf bound_ctrl:1
	v_add_f32_dpp v33, v25, v25 row_ror:8 row_mask:0xf bank_mask:0xf bound_ctrl:1
	ds_read_b128 v[76:79], v13 offset:15360
	v_add_f32_dpp v15, v15, v15 row_ror:2 row_mask:0xf bank_mask:0xf bound_ctrl:1
	ds_read_b128 v[80:83], v13 offset:15616
	ds_read_b128 v[84:87], v13 offset:15872
	v_add_f32_dpp v30, v15, v15 row_ror:1 row_mask:0xf bank_mask:0xf bound_ctrl:1
	ds_read_b128 v[88:91], v13 offset:16128
	ds_read_b128 v[92:95], v13 offset:16384
	ds_write2st64_b32 v12, v32, v33 offset0:16 offset1:18
	s_waitcnt lgkmcnt(6)
	v_pk_fma_f32 v[10:11], v[124:125], v[30:31], v[16:17] op_sel_hi:[1,0,1] neg_lo:[0,1,0] neg_hi:[0,1,0]
	v_pk_fma_f32 v[8:9], v[126:127], v[30:31], v[18:19] op_sel_hi:[1,0,1] neg_lo:[0,1,0] neg_hi:[0,1,0]
	v_pk_mul_f32 v[24:25], v[10:11], v[128:129] op_sel:[0,0] op_sel_hi:[0,1]
	v_pk_fma_f32 v[24:25], v[10:11], v[130:131], v[24:25] op_sel:[1,0,0] op_sel_hi:[1,1,1]
	v_pk_fma_f32 v[24:25], v[8:9], v[132:133], v[24:25] op_sel:[0,0,0] op_sel_hi:[0,1,1]
	v_pk_fma_f32 v[24:25], v[8:9], v[134:135], v[24:25] op_sel:[1,0,0] op_sel_hi:[1,1,1]
	v_pk_mul_f32 v[20:21], v[140:141], v[158:159] op_sel:[0,1] op_sel_hi:[1,1]
	v_pk_mul_f32 v[22:23], v[142:143], v[158:159] op_sel:[0,1] op_sel_hi:[1,1]
	v_add_f32_dpp v15, v24, v24 row_ror:8 row_mask:0xf bank_mask:0xf bound_ctrl:1
	v_pk_fma_f32 v[16:17], v[10:11], v[136:137], v[20:21]
	v_pk_fma_f32 v[18:19], v[8:9], v[138:139], v[22:23]
	v_add_f32_dpp v15, v15, v15 row_ror:4 row_mask:0xf bank_mask:0xf bound_ctrl:1
	v_add_f32_dpp v32, v25, v25 row_ror:8 row_mask:0xf bank_mask:0xf bound_ctrl:1
	ds_read_b128 v[96:99], v13 offset:16640
	v_add_f32_dpp v15, v15, v15 row_ror:2 row_mask:0xf bank_mask:0xf bound_ctrl:1
	ds_read_b128 v[100:103], v13 offset:16896
	ds_read_b128 v[104:107], v13 offset:17152
	v_add_f32_dpp v30, v15, v15 row_ror:1 row_mask:0xf bank_mask:0xf bound_ctrl:1
	ds_read_b128 v[108:111], v13 offset:17408
	ds_read_b128 v[112:115], v13 offset:17664
	s_waitcnt lgkmcnt(5)
	v_pk_fma_f32 v[10:11], v[144:145], v[30:31], v[16:17] op_sel_hi:[1,0,1] neg_lo:[0,1,0] neg_hi:[0,1,0]
	v_pk_fma_f32 v[8:9], v[146:147], v[30:31], v[18:19] op_sel_hi:[1,0,1] neg_lo:[0,1,0] neg_hi:[0,1,0]
	v_pk_mul_f32 v[24:25], v[10:11], v[148:149] op_sel:[0,0] op_sel_hi:[0,1]
	v_pk_fma_f32 v[24:25], v[10:11], v[150:151], v[24:25] op_sel:[1,0,0] op_sel_hi:[1,1,1]
	v_pk_fma_f32 v[24:25], v[8:9], v[152:153], v[24:25] op_sel:[0,0,0] op_sel_hi:[0,1,1]
	v_pk_fma_f32 v[24:25], v[8:9], v[154:155], v[24:25] op_sel:[1,0,0] op_sel_hi:[1,1,1]
	v_pk_mul_f32 v[20:21], v[80:81], v[160:161] op_sel_hi:[1,0]
	v_pk_mul_f32 v[22:23], v[82:83], v[160:161] op_sel_hi:[1,0]
	v_add_f32_dpp v15, v24, v24 row_ror:8 row_mask:0xf bank_mask:0xf bound_ctrl:1
	v_pk_fma_f32 v[16:17], v[10:11], v[76:77], v[20:21]
	v_pk_fma_f32 v[18:19], v[8:9], v[78:79], v[22:23]
	v_add_f32_dpp v15, v15, v15 row_ror:4 row_mask:0xf bank_mask:0xf bound_ctrl:1
	v_add_f32_dpp v33, v25, v25 row_ror:8 row_mask:0xf bank_mask:0xf bound_ctrl:1
	ds_read_b128 v[116:119], v13 offset:17920
	v_add_f32_dpp v15, v15, v15 row_ror:2 row_mask:0xf bank_mask:0xf bound_ctrl:1
	ds_read_b128 v[120:123], v13 offset:18176
	ds_read_b128 v[124:127], v13 offset:18432
	v_add_f32_dpp v30, v15, v15 row_ror:1 row_mask:0xf bank_mask:0xf bound_ctrl:1
	ds_read_b128 v[128:131], v13 offset:18688
	ds_read_b128 v[132:135], v13 offset:18944
	ds_write2st64_b32 v12, v32, v33 offset0:20 offset1:22
	s_waitcnt lgkmcnt(6)
	v_pk_fma_f32 v[10:11], v[84:85], v[30:31], v[16:17] op_sel_hi:[1,0,1] neg_lo:[0,1,0] neg_hi:[0,1,0]
	v_pk_fma_f32 v[8:9], v[86:87], v[30:31], v[18:19] op_sel_hi:[1,0,1] neg_lo:[0,1,0] neg_hi:[0,1,0]
	v_pk_mul_f32 v[24:25], v[10:11], v[88:89] op_sel:[0,0] op_sel_hi:[0,1]
	v_pk_fma_f32 v[24:25], v[10:11], v[90:91], v[24:25] op_sel:[1,0,0] op_sel_hi:[1,1,1]
	v_pk_fma_f32 v[24:25], v[8:9], v[92:93], v[24:25] op_sel:[0,0,0] op_sel_hi:[0,1,1]
	v_pk_fma_f32 v[24:25], v[8:9], v[94:95], v[24:25] op_sel:[1,0,0] op_sel_hi:[1,1,1]
	v_pk_mul_f32 v[20:21], v[100:101], v[160:161] op_sel:[0,1] op_sel_hi:[1,1]
	v_pk_mul_f32 v[22:23], v[102:103], v[160:161] op_sel:[0,1] op_sel_hi:[1,1]
	v_add_f32_dpp v15, v24, v24 row_ror:8 row_mask:0xf bank_mask:0xf bound_ctrl:1
	v_pk_fma_f32 v[16:17], v[10:11], v[96:97], v[20:21]
	v_pk_fma_f32 v[18:19], v[8:9], v[98:99], v[22:23]
	v_add_f32_dpp v15, v15, v15 row_ror:4 row_mask:0xf bank_mask:0xf bound_ctrl:1
	v_add_f32_dpp v32, v25, v25 row_ror:8 row_mask:0xf bank_mask:0xf bound_ctrl:1
	ds_read_b128 v[136:139], v13 offset:19200
	v_add_f32_dpp v15, v15, v15 row_ror:2 row_mask:0xf bank_mask:0xf bound_ctrl:1
	ds_read_b128 v[140:143], v13 offset:19456
	ds_read_b128 v[144:147], v13 offset:19712
	v_add_f32_dpp v30, v15, v15 row_ror:1 row_mask:0xf bank_mask:0xf bound_ctrl:1
	ds_read_b128 v[148:151], v13 offset:19968
	ds_read_b128 v[152:155], v13 offset:20224
	ds_read_b128 v[156:159], v14 offset:64
	s_waitcnt lgkmcnt(6)
	v_pk_fma_f32 v[10:11], v[104:105], v[30:31], v[16:17] op_sel_hi:[1,0,1] neg_lo:[0,1,0] neg_hi:[0,1,0]
	v_pk_fma_f32 v[8:9], v[106:107], v[30:31], v[18:19] op_sel_hi:[1,0,1] neg_lo:[0,1,0] neg_hi:[0,1,0]
	v_pk_mul_f32 v[24:25], v[10:11], v[108:109] op_sel:[0,0] op_sel_hi:[0,1]
	v_pk_fma_f32 v[24:25], v[10:11], v[110:111], v[24:25] op_sel:[1,0,0] op_sel_hi:[1,1,1]
	v_pk_fma_f32 v[24:25], v[8:9], v[112:113], v[24:25] op_sel:[0,0,0] op_sel_hi:[0,1,1]
	v_pk_fma_f32 v[24:25], v[8:9], v[114:115], v[24:25] op_sel:[1,0,0] op_sel_hi:[1,1,1]
	v_pk_mul_f32 v[20:21], v[120:121], v[162:163] op_sel_hi:[1,0]
	v_pk_mul_f32 v[22:23], v[122:123], v[162:163] op_sel_hi:[1,0]
	v_add_f32_dpp v15, v24, v24 row_ror:8 row_mask:0xf bank_mask:0xf bound_ctrl:1
	v_pk_fma_f32 v[16:17], v[10:11], v[116:117], v[20:21]
	v_pk_fma_f32 v[18:19], v[8:9], v[118:119], v[22:23]
	v_add_f32_dpp v15, v15, v15 row_ror:4 row_mask:0xf bank_mask:0xf bound_ctrl:1
	v_add_f32_dpp v33, v25, v25 row_ror:8 row_mask:0xf bank_mask:0xf bound_ctrl:1
	ds_read_b128 v[76:79], v13 offset:20480
	v_add_f32_dpp v15, v15, v15 row_ror:2 row_mask:0xf bank_mask:0xf bound_ctrl:1
	ds_read_b128 v[80:83], v13 offset:20736
	ds_read_b128 v[84:87], v13 offset:20992
	v_add_f32_dpp v30, v15, v15 row_ror:1 row_mask:0xf bank_mask:0xf bound_ctrl:1
	ds_read_b128 v[88:91], v13 offset:21248
	ds_read_b128 v[92:95], v13 offset:21504
	ds_write2st64_b32 v12, v32, v33 offset0:24 offset1:26
	s_waitcnt lgkmcnt(6)
	v_pk_fma_f32 v[10:11], v[124:125], v[30:31], v[16:17] op_sel_hi:[1,0,1] neg_lo:[0,1,0] neg_hi:[0,1,0]
	v_pk_fma_f32 v[8:9], v[126:127], v[30:31], v[18:19] op_sel_hi:[1,0,1] neg_lo:[0,1,0] neg_hi:[0,1,0]
	v_pk_mul_f32 v[24:25], v[10:11], v[128:129] op_sel:[0,0] op_sel_hi:[0,1]
	v_pk_fma_f32 v[24:25], v[10:11], v[130:131], v[24:25] op_sel:[1,0,0] op_sel_hi:[1,1,1]
	v_pk_fma_f32 v[24:25], v[8:9], v[132:133], v[24:25] op_sel:[0,0,0] op_sel_hi:[0,1,1]
	v_pk_fma_f32 v[24:25], v[8:9], v[134:135], v[24:25] op_sel:[1,0,0] op_sel_hi:[1,1,1]
	v_pk_mul_f32 v[20:21], v[140:141], v[162:163] op_sel:[0,1] op_sel_hi:[1,1]
	v_pk_mul_f32 v[22:23], v[142:143], v[162:163] op_sel:[0,1] op_sel_hi:[1,1]
	v_add_f32_dpp v15, v24, v24 row_ror:8 row_mask:0xf bank_mask:0xf bound_ctrl:1
	v_pk_fma_f32 v[16:17], v[10:11], v[136:137], v[20:21]
	v_pk_fma_f32 v[18:19], v[8:9], v[138:139], v[22:23]
	v_add_f32_dpp v15, v15, v15 row_ror:4 row_mask:0xf bank_mask:0xf bound_ctrl:1
	v_add_f32_dpp v32, v25, v25 row_ror:8 row_mask:0xf bank_mask:0xf bound_ctrl:1
	ds_read_b128 v[96:99], v13 offset:21760
	v_add_f32_dpp v15, v15, v15 row_ror:2 row_mask:0xf bank_mask:0xf bound_ctrl:1
	ds_read_b128 v[100:103], v13 offset:22016
	ds_read_b128 v[104:107], v13 offset:22272
	v_add_f32_dpp v30, v15, v15 row_ror:1 row_mask:0xf bank_mask:0xf bound_ctrl:1
	ds_read_b128 v[108:111], v13 offset:22528
	ds_read_b128 v[112:115], v13 offset:22784
	s_waitcnt lgkmcnt(5)
	v_pk_fma_f32 v[10:11], v[144:145], v[30:31], v[16:17] op_sel_hi:[1,0,1] neg_lo:[0,1,0] neg_hi:[0,1,0]
	v_pk_fma_f32 v[8:9], v[146:147], v[30:31], v[18:19] op_sel_hi:[1,0,1] neg_lo:[0,1,0] neg_hi:[0,1,0]
	v_pk_mul_f32 v[24:25], v[10:11], v[148:149] op_sel:[0,0] op_sel_hi:[0,1]
	v_pk_fma_f32 v[24:25], v[10:11], v[150:151], v[24:25] op_sel:[1,0,0] op_sel_hi:[1,1,1]
	v_pk_fma_f32 v[24:25], v[8:9], v[152:153], v[24:25] op_sel:[0,0,0] op_sel_hi:[0,1,1]
	v_pk_fma_f32 v[24:25], v[8:9], v[154:155], v[24:25] op_sel:[1,0,0] op_sel_hi:[1,1,1]
	v_pk_mul_f32 v[20:21], v[80:81], v[156:157] op_sel_hi:[1,0]
	v_pk_mul_f32 v[22:23], v[82:83], v[156:157] op_sel_hi:[1,0]
	v_add_f32_dpp v15, v24, v24 row_ror:8 row_mask:0xf bank_mask:0xf bound_ctrl:1
	v_pk_fma_f32 v[16:17], v[10:11], v[76:77], v[20:21]
	v_pk_fma_f32 v[18:19], v[8:9], v[78:79], v[22:23]
	v_add_f32_dpp v15, v15, v15 row_ror:4 row_mask:0xf bank_mask:0xf bound_ctrl:1
	v_add_f32_dpp v33, v25, v25 row_ror:8 row_mask:0xf bank_mask:0xf bound_ctrl:1
	ds_read_b128 v[116:119], v13 offset:23040
	v_add_f32_dpp v15, v15, v15 row_ror:2 row_mask:0xf bank_mask:0xf bound_ctrl:1
	ds_read_b128 v[120:123], v13 offset:23296
	ds_read_b128 v[124:127], v13 offset:23552
	v_add_f32_dpp v30, v15, v15 row_ror:1 row_mask:0xf bank_mask:0xf bound_ctrl:1
	ds_read_b128 v[128:131], v13 offset:23808
	ds_read_b128 v[132:135], v13 offset:24064
	ds_write2st64_b32 v12, v32, v33 offset0:28 offset1:30
	s_waitcnt lgkmcnt(6)
	v_pk_fma_f32 v[10:11], v[84:85], v[30:31], v[16:17] op_sel_hi:[1,0,1] neg_lo:[0,1,0] neg_hi:[0,1,0]
	v_pk_fma_f32 v[8:9], v[86:87], v[30:31], v[18:19] op_sel_hi:[1,0,1] neg_lo:[0,1,0] neg_hi:[0,1,0]
	v_pk_mul_f32 v[24:25], v[10:11], v[88:89] op_sel:[0,0] op_sel_hi:[0,1]
	v_pk_fma_f32 v[24:25], v[10:11], v[90:91], v[24:25] op_sel:[1,0,0] op_sel_hi:[1,1,1]
	v_pk_fma_f32 v[24:25], v[8:9], v[92:93], v[24:25] op_sel:[0,0,0] op_sel_hi:[0,1,1]
	v_pk_fma_f32 v[24:25], v[8:9], v[94:95], v[24:25] op_sel:[1,0,0] op_sel_hi:[1,1,1]
	v_pk_mul_f32 v[20:21], v[100:101], v[156:157] op_sel:[0,1] op_sel_hi:[1,1]
	v_pk_mul_f32 v[22:23], v[102:103], v[156:157] op_sel:[0,1] op_sel_hi:[1,1]
	v_add_f32_dpp v15, v24, v24 row_ror:8 row_mask:0xf bank_mask:0xf bound_ctrl:1
	v_pk_fma_f32 v[16:17], v[10:11], v[96:97], v[20:21]
	v_pk_fma_f32 v[18:19], v[8:9], v[98:99], v[22:23]
	v_add_f32_dpp v15, v15, v15 row_ror:4 row_mask:0xf bank_mask:0xf bound_ctrl:1
	v_add_f32_dpp v32, v25, v25 row_ror:8 row_mask:0xf bank_mask:0xf bound_ctrl:1
	ds_read_b128 v[136:139], v13 offset:24320
	v_add_f32_dpp v15, v15, v15 row_ror:2 row_mask:0xf bank_mask:0xf bound_ctrl:1
	ds_read_b128 v[140:143], v13 offset:24576
	ds_read_b128 v[144:147], v13 offset:24832
	v_add_f32_dpp v30, v15, v15 row_ror:1 row_mask:0xf bank_mask:0xf bound_ctrl:1
	ds_read_b128 v[148:151], v13 offset:25088
	ds_read_b128 v[152:155], v13 offset:25344
	ds_read_b128 v[160:163], v14 offset:80
	s_waitcnt lgkmcnt(6)
	v_pk_fma_f32 v[10:11], v[104:105], v[30:31], v[16:17] op_sel_hi:[1,0,1] neg_lo:[0,1,0] neg_hi:[0,1,0]
	v_pk_fma_f32 v[8:9], v[106:107], v[30:31], v[18:19] op_sel_hi:[1,0,1] neg_lo:[0,1,0] neg_hi:[0,1,0]
	v_pk_mul_f32 v[24:25], v[10:11], v[108:109] op_sel:[0,0] op_sel_hi:[0,1]
	v_pk_fma_f32 v[24:25], v[10:11], v[110:111], v[24:25] op_sel:[1,0,0] op_sel_hi:[1,1,1]
	v_pk_fma_f32 v[24:25], v[8:9], v[112:113], v[24:25] op_sel:[0,0,0] op_sel_hi:[0,1,1]
	v_pk_fma_f32 v[24:25], v[8:9], v[114:115], v[24:25] op_sel:[1,0,0] op_sel_hi:[1,1,1]
	v_pk_mul_f32 v[20:21], v[120:121], v[158:159] op_sel_hi:[1,0]
	v_pk_mul_f32 v[22:23], v[122:123], v[158:159] op_sel_hi:[1,0]
	v_add_f32_dpp v15, v24, v24 row_ror:8 row_mask:0xf bank_mask:0xf bound_ctrl:1
	v_pk_fma_f32 v[16:17], v[10:11], v[116:117], v[20:21]
	v_pk_fma_f32 v[18:19], v[8:9], v[118:119], v[22:23]
	v_add_f32_dpp v15, v15, v15 row_ror:4 row_mask:0xf bank_mask:0xf bound_ctrl:1
	v_add_f32_dpp v33, v25, v25 row_ror:8 row_mask:0xf bank_mask:0xf bound_ctrl:1
	ds_read_b128 v[76:79], v13 offset:25600
	v_add_f32_dpp v15, v15, v15 row_ror:2 row_mask:0xf bank_mask:0xf bound_ctrl:1
	ds_read_b128 v[80:83], v13 offset:25856
	ds_read_b128 v[84:87], v13 offset:26112
	v_add_f32_dpp v30, v15, v15 row_ror:1 row_mask:0xf bank_mask:0xf bound_ctrl:1
	ds_read_b128 v[88:91], v13 offset:26368
	ds_read_b128 v[92:95], v13 offset:26624
	ds_write2st64_b32 v12, v32, v33 offset0:32 offset1:34
	s_waitcnt lgkmcnt(6)
	v_pk_fma_f32 v[10:11], v[124:125], v[30:31], v[16:17] op_sel_hi:[1,0,1] neg_lo:[0,1,0] neg_hi:[0,1,0]
	v_pk_fma_f32 v[8:9], v[126:127], v[30:31], v[18:19] op_sel_hi:[1,0,1] neg_lo:[0,1,0] neg_hi:[0,1,0]
	v_pk_mul_f32 v[24:25], v[10:11], v[128:129] op_sel:[0,0] op_sel_hi:[0,1]
	v_pk_fma_f32 v[24:25], v[10:11], v[130:131], v[24:25] op_sel:[1,0,0] op_sel_hi:[1,1,1]
	v_pk_fma_f32 v[24:25], v[8:9], v[132:133], v[24:25] op_sel:[0,0,0] op_sel_hi:[0,1,1]
	v_pk_fma_f32 v[24:25], v[8:9], v[134:135], v[24:25] op_sel:[1,0,0] op_sel_hi:[1,1,1]
	v_pk_mul_f32 v[20:21], v[140:141], v[158:159] op_sel:[0,1] op_sel_hi:[1,1]
	v_pk_mul_f32 v[22:23], v[142:143], v[158:159] op_sel:[0,1] op_sel_hi:[1,1]
	v_add_f32_dpp v15, v24, v24 row_ror:8 row_mask:0xf bank_mask:0xf bound_ctrl:1
	v_pk_fma_f32 v[16:17], v[10:11], v[136:137], v[20:21]
	v_pk_fma_f32 v[18:19], v[8:9], v[138:139], v[22:23]
	v_add_f32_dpp v15, v15, v15 row_ror:4 row_mask:0xf bank_mask:0xf bound_ctrl:1
	v_add_f32_dpp v32, v25, v25 row_ror:8 row_mask:0xf bank_mask:0xf bound_ctrl:1
	ds_read_b128 v[96:99], v13 offset:26880
	v_add_f32_dpp v15, v15, v15 row_ror:2 row_mask:0xf bank_mask:0xf bound_ctrl:1
	ds_read_b128 v[100:103], v13 offset:27136
	ds_read_b128 v[104:107], v13 offset:27392
	v_add_f32_dpp v30, v15, v15 row_ror:1 row_mask:0xf bank_mask:0xf bound_ctrl:1
	ds_read_b128 v[108:111], v13 offset:27648
	ds_read_b128 v[112:115], v13 offset:27904
	s_waitcnt lgkmcnt(5)
	v_pk_fma_f32 v[10:11], v[144:145], v[30:31], v[16:17] op_sel_hi:[1,0,1] neg_lo:[0,1,0] neg_hi:[0,1,0]
	v_pk_fma_f32 v[8:9], v[146:147], v[30:31], v[18:19] op_sel_hi:[1,0,1] neg_lo:[0,1,0] neg_hi:[0,1,0]
	v_pk_mul_f32 v[24:25], v[10:11], v[148:149] op_sel:[0,0] op_sel_hi:[0,1]
	v_pk_fma_f32 v[24:25], v[10:11], v[150:151], v[24:25] op_sel:[1,0,0] op_sel_hi:[1,1,1]
	v_pk_fma_f32 v[24:25], v[8:9], v[152:153], v[24:25] op_sel:[0,0,0] op_sel_hi:[0,1,1]
	v_pk_fma_f32 v[24:25], v[8:9], v[154:155], v[24:25] op_sel:[1,0,0] op_sel_hi:[1,1,1]
	v_pk_mul_f32 v[20:21], v[80:81], v[160:161] op_sel_hi:[1,0]
	v_pk_mul_f32 v[22:23], v[82:83], v[160:161] op_sel_hi:[1,0]
	v_add_f32_dpp v15, v24, v24 row_ror:8 row_mask:0xf bank_mask:0xf bound_ctrl:1
	v_pk_fma_f32 v[16:17], v[10:11], v[76:77], v[20:21]
	v_pk_fma_f32 v[18:19], v[8:9], v[78:79], v[22:23]
	v_add_f32_dpp v15, v15, v15 row_ror:4 row_mask:0xf bank_mask:0xf bound_ctrl:1
	v_add_f32_dpp v33, v25, v25 row_ror:8 row_mask:0xf bank_mask:0xf bound_ctrl:1
	ds_read_b128 v[116:119], v13 offset:28160
	v_add_f32_dpp v15, v15, v15 row_ror:2 row_mask:0xf bank_mask:0xf bound_ctrl:1
	ds_read_b128 v[120:123], v13 offset:28416
	ds_read_b128 v[124:127], v13 offset:28672
	v_add_f32_dpp v30, v15, v15 row_ror:1 row_mask:0xf bank_mask:0xf bound_ctrl:1
	ds_read_b128 v[128:131], v13 offset:28928
	ds_read_b128 v[132:135], v13 offset:29184
	ds_write2st64_b32 v12, v32, v33 offset0:36 offset1:38
	s_waitcnt lgkmcnt(6)
	v_pk_fma_f32 v[10:11], v[84:85], v[30:31], v[16:17] op_sel_hi:[1,0,1] neg_lo:[0,1,0] neg_hi:[0,1,0]
	v_pk_fma_f32 v[8:9], v[86:87], v[30:31], v[18:19] op_sel_hi:[1,0,1] neg_lo:[0,1,0] neg_hi:[0,1,0]
	v_pk_mul_f32 v[24:25], v[10:11], v[88:89] op_sel:[0,0] op_sel_hi:[0,1]
	v_pk_fma_f32 v[24:25], v[10:11], v[90:91], v[24:25] op_sel:[1,0,0] op_sel_hi:[1,1,1]
	v_pk_fma_f32 v[24:25], v[8:9], v[92:93], v[24:25] op_sel:[0,0,0] op_sel_hi:[0,1,1]
	v_pk_fma_f32 v[24:25], v[8:9], v[94:95], v[24:25] op_sel:[1,0,0] op_sel_hi:[1,1,1]
	v_pk_mul_f32 v[20:21], v[100:101], v[160:161] op_sel:[0,1] op_sel_hi:[1,1]
	v_pk_mul_f32 v[22:23], v[102:103], v[160:161] op_sel:[0,1] op_sel_hi:[1,1]
	v_add_f32_dpp v15, v24, v24 row_ror:8 row_mask:0xf bank_mask:0xf bound_ctrl:1
	v_pk_fma_f32 v[16:17], v[10:11], v[96:97], v[20:21]
	v_pk_fma_f32 v[18:19], v[8:9], v[98:99], v[22:23]
	v_add_f32_dpp v15, v15, v15 row_ror:4 row_mask:0xf bank_mask:0xf bound_ctrl:1
	v_add_f32_dpp v32, v25, v25 row_ror:8 row_mask:0xf bank_mask:0xf bound_ctrl:1
	ds_read_b128 v[136:139], v13 offset:29440
	v_add_f32_dpp v15, v15, v15 row_ror:2 row_mask:0xf bank_mask:0xf bound_ctrl:1
	ds_read_b128 v[140:143], v13 offset:29696
	ds_read_b128 v[144:147], v13 offset:29952
	v_add_f32_dpp v30, v15, v15 row_ror:1 row_mask:0xf bank_mask:0xf bound_ctrl:1
	ds_read_b128 v[148:151], v13 offset:30208
	ds_read_b128 v[152:155], v13 offset:30464
	ds_read_b128 v[156:159], v14 offset:96
	s_waitcnt lgkmcnt(6)
	v_pk_fma_f32 v[10:11], v[104:105], v[30:31], v[16:17] op_sel_hi:[1,0,1] neg_lo:[0,1,0] neg_hi:[0,1,0]
	v_pk_fma_f32 v[8:9], v[106:107], v[30:31], v[18:19] op_sel_hi:[1,0,1] neg_lo:[0,1,0] neg_hi:[0,1,0]
	v_pk_mul_f32 v[24:25], v[10:11], v[108:109] op_sel:[0,0] op_sel_hi:[0,1]
	v_pk_fma_f32 v[24:25], v[10:11], v[110:111], v[24:25] op_sel:[1,0,0] op_sel_hi:[1,1,1]
	v_pk_fma_f32 v[24:25], v[8:9], v[112:113], v[24:25] op_sel:[0,0,0] op_sel_hi:[0,1,1]
	v_pk_fma_f32 v[24:25], v[8:9], v[114:115], v[24:25] op_sel:[1,0,0] op_sel_hi:[1,1,1]
	v_pk_mul_f32 v[20:21], v[120:121], v[162:163] op_sel_hi:[1,0]
	v_pk_mul_f32 v[22:23], v[122:123], v[162:163] op_sel_hi:[1,0]
	v_add_f32_dpp v15, v24, v24 row_ror:8 row_mask:0xf bank_mask:0xf bound_ctrl:1
	v_pk_fma_f32 v[16:17], v[10:11], v[116:117], v[20:21]
	v_pk_fma_f32 v[18:19], v[8:9], v[118:119], v[22:23]
	v_add_f32_dpp v15, v15, v15 row_ror:4 row_mask:0xf bank_mask:0xf bound_ctrl:1
	v_add_f32_dpp v33, v25, v25 row_ror:8 row_mask:0xf bank_mask:0xf bound_ctrl:1
	ds_read_b128 v[76:79], v13 offset:30720
	v_add_f32_dpp v15, v15, v15 row_ror:2 row_mask:0xf bank_mask:0xf bound_ctrl:1
	ds_read_b128 v[80:83], v13 offset:30976
	ds_read_b128 v[84:87], v13 offset:31232
	v_add_f32_dpp v30, v15, v15 row_ror:1 row_mask:0xf bank_mask:0xf bound_ctrl:1
	ds_read_b128 v[88:91], v13 offset:31488
	ds_read_b128 v[92:95], v13 offset:31744
	ds_write2st64_b32 v12, v32, v33 offset0:40 offset1:42
	s_waitcnt lgkmcnt(6)
	v_pk_fma_f32 v[10:11], v[124:125], v[30:31], v[16:17] op_sel_hi:[1,0,1] neg_lo:[0,1,0] neg_hi:[0,1,0]
	v_pk_fma_f32 v[8:9], v[126:127], v[30:31], v[18:19] op_sel_hi:[1,0,1] neg_lo:[0,1,0] neg_hi:[0,1,0]
	v_pk_mul_f32 v[24:25], v[10:11], v[128:129] op_sel:[0,0] op_sel_hi:[0,1]
	v_pk_fma_f32 v[24:25], v[10:11], v[130:131], v[24:25] op_sel:[1,0,0] op_sel_hi:[1,1,1]
	v_pk_fma_f32 v[24:25], v[8:9], v[132:133], v[24:25] op_sel:[0,0,0] op_sel_hi:[0,1,1]
	v_pk_fma_f32 v[24:25], v[8:9], v[134:135], v[24:25] op_sel:[1,0,0] op_sel_hi:[1,1,1]
	v_pk_mul_f32 v[20:21], v[140:141], v[162:163] op_sel:[0,1] op_sel_hi:[1,1]
	v_pk_mul_f32 v[22:23], v[142:143], v[162:163] op_sel:[0,1] op_sel_hi:[1,1]
	v_add_f32_dpp v15, v24, v24 row_ror:8 row_mask:0xf bank_mask:0xf bound_ctrl:1
	v_pk_fma_f32 v[16:17], v[10:11], v[136:137], v[20:21]
	v_pk_fma_f32 v[18:19], v[8:9], v[138:139], v[22:23]
	v_add_f32_dpp v15, v15, v15 row_ror:4 row_mask:0xf bank_mask:0xf bound_ctrl:1
	v_add_f32_dpp v32, v25, v25 row_ror:8 row_mask:0xf bank_mask:0xf bound_ctrl:1
	ds_read_b128 v[96:99], v13 offset:32000
	v_add_f32_dpp v15, v15, v15 row_ror:2 row_mask:0xf bank_mask:0xf bound_ctrl:1
	ds_read_b128 v[100:103], v13 offset:32256
	ds_read_b128 v[104:107], v13 offset:32512
	v_add_f32_dpp v30, v15, v15 row_ror:1 row_mask:0xf bank_mask:0xf bound_ctrl:1
	ds_read_b128 v[108:111], v13 offset:32768
	ds_read_b128 v[112:115], v13 offset:33024
	s_waitcnt lgkmcnt(5)
	v_pk_fma_f32 v[10:11], v[144:145], v[30:31], v[16:17] op_sel_hi:[1,0,1] neg_lo:[0,1,0] neg_hi:[0,1,0]
	v_pk_fma_f32 v[8:9], v[146:147], v[30:31], v[18:19] op_sel_hi:[1,0,1] neg_lo:[0,1,0] neg_hi:[0,1,0]
	v_pk_mul_f32 v[24:25], v[10:11], v[148:149] op_sel:[0,0] op_sel_hi:[0,1]
	v_pk_fma_f32 v[24:25], v[10:11], v[150:151], v[24:25] op_sel:[1,0,0] op_sel_hi:[1,1,1]
	v_pk_fma_f32 v[24:25], v[8:9], v[152:153], v[24:25] op_sel:[0,0,0] op_sel_hi:[0,1,1]
	v_pk_fma_f32 v[24:25], v[8:9], v[154:155], v[24:25] op_sel:[1,0,0] op_sel_hi:[1,1,1]
	v_pk_mul_f32 v[20:21], v[80:81], v[156:157] op_sel_hi:[1,0]
	v_pk_mul_f32 v[22:23], v[82:83], v[156:157] op_sel_hi:[1,0]
	v_add_f32_dpp v15, v24, v24 row_ror:8 row_mask:0xf bank_mask:0xf bound_ctrl:1
	v_pk_fma_f32 v[16:17], v[10:11], v[76:77], v[20:21]
	v_pk_fma_f32 v[18:19], v[8:9], v[78:79], v[22:23]
	v_add_f32_dpp v15, v15, v15 row_ror:4 row_mask:0xf bank_mask:0xf bound_ctrl:1
	v_add_f32_dpp v33, v25, v25 row_ror:8 row_mask:0xf bank_mask:0xf bound_ctrl:1
	ds_read_b128 v[116:119], v13 offset:33280
	v_add_f32_dpp v15, v15, v15 row_ror:2 row_mask:0xf bank_mask:0xf bound_ctrl:1
	ds_read_b128 v[120:123], v13 offset:33536
	ds_read_b128 v[124:127], v13 offset:33792
	v_add_f32_dpp v30, v15, v15 row_ror:1 row_mask:0xf bank_mask:0xf bound_ctrl:1
	ds_read_b128 v[128:131], v13 offset:34048
	ds_read_b128 v[132:135], v13 offset:34304
	ds_write2st64_b32 v12, v32, v33 offset0:44 offset1:46
	s_waitcnt lgkmcnt(6)
	v_pk_fma_f32 v[10:11], v[84:85], v[30:31], v[16:17] op_sel_hi:[1,0,1] neg_lo:[0,1,0] neg_hi:[0,1,0]
	v_pk_fma_f32 v[8:9], v[86:87], v[30:31], v[18:19] op_sel_hi:[1,0,1] neg_lo:[0,1,0] neg_hi:[0,1,0]
	v_pk_mul_f32 v[24:25], v[10:11], v[88:89] op_sel:[0,0] op_sel_hi:[0,1]
	v_pk_fma_f32 v[24:25], v[10:11], v[90:91], v[24:25] op_sel:[1,0,0] op_sel_hi:[1,1,1]
	v_pk_fma_f32 v[24:25], v[8:9], v[92:93], v[24:25] op_sel:[0,0,0] op_sel_hi:[0,1,1]
	v_pk_fma_f32 v[24:25], v[8:9], v[94:95], v[24:25] op_sel:[1,0,0] op_sel_hi:[1,1,1]
	v_pk_mul_f32 v[20:21], v[100:101], v[156:157] op_sel:[0,1] op_sel_hi:[1,1]
	v_pk_mul_f32 v[22:23], v[102:103], v[156:157] op_sel:[0,1] op_sel_hi:[1,1]
	v_add_f32_dpp v15, v24, v24 row_ror:8 row_mask:0xf bank_mask:0xf bound_ctrl:1
	v_pk_fma_f32 v[16:17], v[10:11], v[96:97], v[20:21]
	v_pk_fma_f32 v[18:19], v[8:9], v[98:99], v[22:23]
	v_add_f32_dpp v15, v15, v15 row_ror:4 row_mask:0xf bank_mask:0xf bound_ctrl:1
	v_add_f32_dpp v32, v25, v25 row_ror:8 row_mask:0xf bank_mask:0xf bound_ctrl:1
	ds_read_b128 v[136:139], v13 offset:34560
	v_add_f32_dpp v15, v15, v15 row_ror:2 row_mask:0xf bank_mask:0xf bound_ctrl:1
	ds_read_b128 v[140:143], v13 offset:34816
	ds_read_b128 v[144:147], v13 offset:35072
	v_add_f32_dpp v30, v15, v15 row_ror:1 row_mask:0xf bank_mask:0xf bound_ctrl:1
	ds_read_b128 v[148:151], v13 offset:35328
	ds_read_b128 v[152:155], v13 offset:35584
	ds_read_b128 v[160:163], v14 offset:112
	s_waitcnt lgkmcnt(6)
	v_pk_fma_f32 v[10:11], v[104:105], v[30:31], v[16:17] op_sel_hi:[1,0,1] neg_lo:[0,1,0] neg_hi:[0,1,0]
	v_pk_fma_f32 v[8:9], v[106:107], v[30:31], v[18:19] op_sel_hi:[1,0,1] neg_lo:[0,1,0] neg_hi:[0,1,0]
	v_pk_mul_f32 v[24:25], v[10:11], v[108:109] op_sel:[0,0] op_sel_hi:[0,1]
	v_pk_fma_f32 v[24:25], v[10:11], v[110:111], v[24:25] op_sel:[1,0,0] op_sel_hi:[1,1,1]
	v_pk_fma_f32 v[24:25], v[8:9], v[112:113], v[24:25] op_sel:[0,0,0] op_sel_hi:[0,1,1]
	v_pk_fma_f32 v[24:25], v[8:9], v[114:115], v[24:25] op_sel:[1,0,0] op_sel_hi:[1,1,1]
	v_pk_mul_f32 v[20:21], v[120:121], v[158:159] op_sel_hi:[1,0]
	v_pk_mul_f32 v[22:23], v[122:123], v[158:159] op_sel_hi:[1,0]
	v_add_f32_dpp v15, v24, v24 row_ror:8 row_mask:0xf bank_mask:0xf bound_ctrl:1
	v_pk_fma_f32 v[16:17], v[10:11], v[116:117], v[20:21]
	v_pk_fma_f32 v[18:19], v[8:9], v[118:119], v[22:23]
	v_add_f32_dpp v15, v15, v15 row_ror:4 row_mask:0xf bank_mask:0xf bound_ctrl:1
	v_add_f32_dpp v33, v25, v25 row_ror:8 row_mask:0xf bank_mask:0xf bound_ctrl:1
	ds_read_b128 v[76:79], v13 offset:35840
	v_add_f32_dpp v15, v15, v15 row_ror:2 row_mask:0xf bank_mask:0xf bound_ctrl:1
	ds_read_b128 v[80:83], v13 offset:36096
	ds_read_b128 v[84:87], v13 offset:36352
	v_add_f32_dpp v30, v15, v15 row_ror:1 row_mask:0xf bank_mask:0xf bound_ctrl:1
	ds_read_b128 v[88:91], v13 offset:36608
	ds_read_b128 v[92:95], v13 offset:36864
	ds_write2st64_b32 v12, v32, v33 offset0:48 offset1:50
	s_waitcnt lgkmcnt(6)
	v_pk_fma_f32 v[10:11], v[124:125], v[30:31], v[16:17] op_sel_hi:[1,0,1] neg_lo:[0,1,0] neg_hi:[0,1,0]
	v_pk_fma_f32 v[8:9], v[126:127], v[30:31], v[18:19] op_sel_hi:[1,0,1] neg_lo:[0,1,0] neg_hi:[0,1,0]
	v_pk_mul_f32 v[24:25], v[10:11], v[128:129] op_sel:[0,0] op_sel_hi:[0,1]
	v_pk_fma_f32 v[24:25], v[10:11], v[130:131], v[24:25] op_sel:[1,0,0] op_sel_hi:[1,1,1]
	v_pk_fma_f32 v[24:25], v[8:9], v[132:133], v[24:25] op_sel:[0,0,0] op_sel_hi:[0,1,1]
	v_pk_fma_f32 v[24:25], v[8:9], v[134:135], v[24:25] op_sel:[1,0,0] op_sel_hi:[1,1,1]
	v_pk_mul_f32 v[20:21], v[140:141], v[158:159] op_sel:[0,1] op_sel_hi:[1,1]
	v_pk_mul_f32 v[22:23], v[142:143], v[158:159] op_sel:[0,1] op_sel_hi:[1,1]
	v_add_f32_dpp v15, v24, v24 row_ror:8 row_mask:0xf bank_mask:0xf bound_ctrl:1
	v_pk_fma_f32 v[16:17], v[10:11], v[136:137], v[20:21]
	v_pk_fma_f32 v[18:19], v[8:9], v[138:139], v[22:23]
	v_add_f32_dpp v15, v15, v15 row_ror:4 row_mask:0xf bank_mask:0xf bound_ctrl:1
	v_add_f32_dpp v32, v25, v25 row_ror:8 row_mask:0xf bank_mask:0xf bound_ctrl:1
	ds_read_b128 v[96:99], v13 offset:37120
	v_add_f32_dpp v15, v15, v15 row_ror:2 row_mask:0xf bank_mask:0xf bound_ctrl:1
	ds_read_b128 v[100:103], v13 offset:37376
	ds_read_b128 v[104:107], v13 offset:37632
	v_add_f32_dpp v30, v15, v15 row_ror:1 row_mask:0xf bank_mask:0xf bound_ctrl:1
	ds_read_b128 v[108:111], v13 offset:37888
	ds_read_b128 v[112:115], v13 offset:38144
	s_waitcnt lgkmcnt(5)
	v_pk_fma_f32 v[10:11], v[144:145], v[30:31], v[16:17] op_sel_hi:[1,0,1] neg_lo:[0,1,0] neg_hi:[0,1,0]
	v_pk_fma_f32 v[8:9], v[146:147], v[30:31], v[18:19] op_sel_hi:[1,0,1] neg_lo:[0,1,0] neg_hi:[0,1,0]
	v_pk_mul_f32 v[24:25], v[10:11], v[148:149] op_sel:[0,0] op_sel_hi:[0,1]
	v_pk_fma_f32 v[24:25], v[10:11], v[150:151], v[24:25] op_sel:[1,0,0] op_sel_hi:[1,1,1]
	v_pk_fma_f32 v[24:25], v[8:9], v[152:153], v[24:25] op_sel:[0,0,0] op_sel_hi:[0,1,1]
	v_pk_fma_f32 v[24:25], v[8:9], v[154:155], v[24:25] op_sel:[1,0,0] op_sel_hi:[1,1,1]
	v_pk_mul_f32 v[20:21], v[80:81], v[160:161] op_sel_hi:[1,0]
	v_pk_mul_f32 v[22:23], v[82:83], v[160:161] op_sel_hi:[1,0]
	v_add_f32_dpp v15, v24, v24 row_ror:8 row_mask:0xf bank_mask:0xf bound_ctrl:1
	v_pk_fma_f32 v[16:17], v[10:11], v[76:77], v[20:21]
	v_pk_fma_f32 v[18:19], v[8:9], v[78:79], v[22:23]
	v_add_f32_dpp v15, v15, v15 row_ror:4 row_mask:0xf bank_mask:0xf bound_ctrl:1
	v_add_f32_dpp v33, v25, v25 row_ror:8 row_mask:0xf bank_mask:0xf bound_ctrl:1
	ds_read_b128 v[116:119], v13 offset:38400
	v_add_f32_dpp v15, v15, v15 row_ror:2 row_mask:0xf bank_mask:0xf bound_ctrl:1
	ds_read_b128 v[120:123], v13 offset:38656
	ds_read_b128 v[124:127], v13 offset:38912
	v_add_f32_dpp v30, v15, v15 row_ror:1 row_mask:0xf bank_mask:0xf bound_ctrl:1
	ds_read_b128 v[128:131], v13 offset:39168
	ds_read_b128 v[132:135], v13 offset:39424
	ds_write2st64_b32 v12, v32, v33 offset0:52 offset1:54
	s_waitcnt lgkmcnt(6)
	v_pk_fma_f32 v[10:11], v[84:85], v[30:31], v[16:17] op_sel_hi:[1,0,1] neg_lo:[0,1,0] neg_hi:[0,1,0]
	v_pk_fma_f32 v[8:9], v[86:87], v[30:31], v[18:19] op_sel_hi:[1,0,1] neg_lo:[0,1,0] neg_hi:[0,1,0]
	v_pk_mul_f32 v[24:25], v[10:11], v[88:89] op_sel:[0,0] op_sel_hi:[0,1]
	v_pk_fma_f32 v[24:25], v[10:11], v[90:91], v[24:25] op_sel:[1,0,0] op_sel_hi:[1,1,1]
	v_pk_fma_f32 v[24:25], v[8:9], v[92:93], v[24:25] op_sel:[0,0,0] op_sel_hi:[0,1,1]
	v_pk_fma_f32 v[24:25], v[8:9], v[94:95], v[24:25] op_sel:[1,0,0] op_sel_hi:[1,1,1]
	v_pk_mul_f32 v[20:21], v[100:101], v[160:161] op_sel:[0,1] op_sel_hi:[1,1]
	v_pk_mul_f32 v[22:23], v[102:103], v[160:161] op_sel:[0,1] op_sel_hi:[1,1]
	v_add_f32_dpp v15, v24, v24 row_ror:8 row_mask:0xf bank_mask:0xf bound_ctrl:1
	v_pk_fma_f32 v[16:17], v[10:11], v[96:97], v[20:21]
	v_pk_fma_f32 v[18:19], v[8:9], v[98:99], v[22:23]
	v_add_f32_dpp v15, v15, v15 row_ror:4 row_mask:0xf bank_mask:0xf bound_ctrl:1
	v_add_f32_dpp v32, v25, v25 row_ror:8 row_mask:0xf bank_mask:0xf bound_ctrl:1
	ds_read_b128 v[136:139], v13 offset:39680
	v_add_f32_dpp v15, v15, v15 row_ror:2 row_mask:0xf bank_mask:0xf bound_ctrl:1
	ds_read_b128 v[140:143], v13 offset:39936
	ds_read_b128 v[144:147], v13 offset:40192
	v_add_f32_dpp v30, v15, v15 row_ror:1 row_mask:0xf bank_mask:0xf bound_ctrl:1
	ds_read_b128 v[148:151], v13 offset:40448
	ds_read_b128 v[152:155], v13 offset:40704
	s_waitcnt lgkmcnt(5)
	v_pk_fma_f32 v[10:11], v[104:105], v[30:31], v[16:17] op_sel_hi:[1,0,1] neg_lo:[0,1,0] neg_hi:[0,1,0]
	v_pk_fma_f32 v[8:9], v[106:107], v[30:31], v[18:19] op_sel_hi:[1,0,1] neg_lo:[0,1,0] neg_hi:[0,1,0]
	v_pk_mul_f32 v[24:25], v[10:11], v[108:109] op_sel:[0,0] op_sel_hi:[0,1]
	v_pk_fma_f32 v[24:25], v[10:11], v[110:111], v[24:25] op_sel:[1,0,0] op_sel_hi:[1,1,1]
	v_pk_fma_f32 v[24:25], v[8:9], v[112:113], v[24:25] op_sel:[0,0,0] op_sel_hi:[0,1,1]
	v_pk_fma_f32 v[24:25], v[8:9], v[114:115], v[24:25] op_sel:[1,0,0] op_sel_hi:[1,1,1]
	v_pk_mul_f32 v[20:21], v[120:121], v[162:163] op_sel_hi:[1,0]
	v_pk_mul_f32 v[22:23], v[122:123], v[162:163] op_sel_hi:[1,0]
	v_add_f32_dpp v15, v24, v24 row_ror:8 row_mask:0xf bank_mask:0xf bound_ctrl:1
	v_pk_fma_f32 v[16:17], v[10:11], v[116:117], v[20:21]
	v_pk_fma_f32 v[18:19], v[8:9], v[118:119], v[22:23]
	v_add_f32_dpp v15, v15, v15 row_ror:4 row_mask:0xf bank_mask:0xf bound_ctrl:1
	v_add_f32_dpp v33, v25, v25 row_ror:8 row_mask:0xf bank_mask:0xf bound_ctrl:1
	s_nop 0
	v_add_f32_dpp v15, v15, v15 row_ror:2 row_mask:0xf bank_mask:0xf bound_ctrl:1
	s_nop 1
	v_add_f32_dpp v30, v15, v15 row_ror:1 row_mask:0xf bank_mask:0xf bound_ctrl:1
	ds_write2st64_b32 v12, v32, v33 offset0:56 offset1:58
	s_waitcnt lgkmcnt(1)
	v_pk_fma_f32 v[10:11], v[124:125], v[30:31], v[16:17] op_sel_hi:[1,0,1] neg_lo:[0,1,0] neg_hi:[0,1,0]
	v_pk_fma_f32 v[8:9], v[126:127], v[30:31], v[18:19] op_sel_hi:[1,0,1] neg_lo:[0,1,0] neg_hi:[0,1,0]
	v_pk_mul_f32 v[24:25], v[10:11], v[128:129] op_sel:[0,0] op_sel_hi:[0,1]
	v_pk_fma_f32 v[24:25], v[10:11], v[130:131], v[24:25] op_sel:[1,0,0] op_sel_hi:[1,1,1]
	v_pk_fma_f32 v[24:25], v[8:9], v[132:133], v[24:25] op_sel:[0,0,0] op_sel_hi:[0,1,1]
	v_pk_fma_f32 v[24:25], v[8:9], v[134:135], v[24:25] op_sel:[1,0,0] op_sel_hi:[1,1,1]
	v_pk_mul_f32 v[20:21], v[140:141], v[162:163] op_sel:[0,1] op_sel_hi:[1,1]
	v_pk_mul_f32 v[22:23], v[142:143], v[162:163] op_sel:[0,1] op_sel_hi:[1,1]
	v_add_f32_dpp v15, v24, v24 row_ror:8 row_mask:0xf bank_mask:0xf bound_ctrl:1
	v_pk_fma_f32 v[16:17], v[10:11], v[136:137], v[20:21]
	v_pk_fma_f32 v[18:19], v[8:9], v[138:139], v[22:23]
	v_add_f32_dpp v15, v15, v15 row_ror:4 row_mask:0xf bank_mask:0xf bound_ctrl:1
	v_add_f32_dpp v32, v25, v25 row_ror:8 row_mask:0xf bank_mask:0xf bound_ctrl:1
	s_nop 0
	v_add_f32_dpp v15, v15, v15 row_ror:2 row_mask:0xf bank_mask:0xf bound_ctrl:1
	s_nop 1
	v_add_f32_dpp v30, v15, v15 row_ror:1 row_mask:0xf bank_mask:0xf bound_ctrl:1
	v_pk_fma_f32 v[10:11], v[144:145], v[30:31], v[16:17] op_sel_hi:[1,0,1] neg_lo:[0,1,0] neg_hi:[0,1,0]
	v_pk_fma_f32 v[8:9], v[146:147], v[30:31], v[18:19] op_sel_hi:[1,0,1] neg_lo:[0,1,0] neg_hi:[0,1,0]
	v_pk_mul_f32 v[24:25], v[10:11], v[148:149] op_sel:[0,0] op_sel_hi:[0,1]
	v_pk_fma_f32 v[24:25], v[10:11], v[150:151], v[24:25] op_sel:[1,0,0] op_sel_hi:[1,1,1]
	v_pk_fma_f32 v[24:25], v[8:9], v[152:153], v[24:25] op_sel:[0,0,0] op_sel_hi:[0,1,1]
	v_pk_fma_f32 v[24:25], v[8:9], v[154:155], v[24:25] op_sel:[1,0,0] op_sel_hi:[1,1,1]
	s_nop 1
	v_add_f32_dpp v33, v25, v25 row_ror:8 row_mask:0xf bank_mask:0xf bound_ctrl:1
	ds_write2st64_b32 v12, v32, v33 offset0:60 offset1:62
.Lsc_S_sync:
	s_add_i32 s6, s6, 1
	s_add_i32 s5, s5, 32
	s_waitcnt lgkmcnt(0)
	s_barrier
	s_cmp_lg_u32 s6, 0x102
	s_cbranch_scc1 .Lsc_S_loop
	s_branch .Lsc_item_end
.Lsc_G:
	v_add_u32_e32 v1, 0xffffff00, v173
	v_lshrrev_b32_e32 v2, 3, v1
	v_and_b32_e32 v3, 7, v1
	s_and_b32 s8, s4, 7
	s_bfe_u32 s10, s4, 0x20003
	s_lshr_b32 s11, s4, 7
	s_bfe_u32 s9, s4, 0x20005
	s_lshl_b32 s9, s9, 13
	v_readlane_b32 s50, v242, 0
	v_readlane_b32 s51, v242, 1
	v_readlane_b32 s16, v242, 62
	s_load_dwordx4 s[12:15], s[50:51], 0x68
	s_add_u32 s36, s90, 0x5e00000
	s_addc_u32 s37, s91, 0
	s_add_u32 s38, s90, 0x7e00000
	s_addc_u32 s39, s91, 0
	s_add_u32 s44, s90, 0x9e00000
	s_addc_u32 s45, s91, 0
	s_add_u32 s46, s90, 0x1c00000
	s_addc_u32 s47, s91, 0
	s_lshl_b32 s68, s11, 25
	s_add_u32 s69, s68, 0x13e00000
	s_add_u32 s40, s90, s69
	s_addc_u32 s41, s91, 0
	s_add_u32 s69, s68, 0x17e00000
	s_add_u32 s42, s90, s69
	s_addc_u32 s43, s91, 0
	s_lshl_b32 s68, s11, 26
	s_add_u32 s68, s68, 0xbe00000
	s_add_u32 s48, s90, s68
	s_addc_u32 s49, s91, 0
	s_cmp_eq_u32 s11, 0
	s_mov_b32 s54, 0x8000
	s_movk_i32 s55, 0x400
	s_mov_b32 s64, 0x10000
	s_cselect_b32 s54, s54, 0xffff8000
	s_cselect_b32 s55, s55, 0xfffffc00
	s_cselect_b32 s64, s64, 0xffff0000
	s_cselect_b64 vcc, -1, 0
	v_sub_u32_e32 v4, 0x1fff, v2
	s_nop 3
	v_cndmask_b32_e32 v4, v4, v2, vcc
	v_add_u32_e32 v4, s9, v4
	s_lshl_b32 s68, s8, 7
	v_lshlrev_b32_e32 v5, 10, v4
	v_lshl_add_u32 v5, v3, 3, v5
	v_add_u32_e32 v5, s68, v5
	s_lshl_b32 s69, s8, 2
	v_lshlrev_b32_e32 v6, 5, v4
	v_add_u32_e32 v6, s69, v6
	s_lshl_b32 s69, s10, 5
	s_add_i32 s69, s69, s68
	v_lshlrev_b32_e32 v9, 10, v4
	v_lshl_add_u32 v9, v3, 2, v9
	v_add_u32_e32 v9, s69, v9
	s_lshl_b32 s69, s69, 1
	v_lshlrev_b32_e32 v7, 11, v4
	v_lshl_add_u32 v7, v3, 3, v7
	v_add_u32_e32 v7, s69, v7
	v_mul_u32_u24_e32 v8, 1280, v2
	v_lshl_add_u32 v8, v3, 4, v8
	v_add_u32_e32 v138, 768, v8
	v_add_u32_e32 v140, 43008, v8
	v_add_u32_e32 v139, -1, v2
	v_cmp_eq_u32_e32 vcc, 0, v2
	v_mov_b32_e32 v106, 32
	s_nop 1
	v_cndmask_b32_e32 v139, v139, v106, vcc
	v_mul_u32_u24_e32 v139, 1280, v139
	v_lshl_add_u32 v139, v3, 4, v139
	v_add_u32_e32 v141, 43008, v139
	v_add_u32_e32 v139, 768, v139
	v_mul_u32_u24_e32 v142, 288, v3
	v_lshl_add_u32 v142, v2, 2, v142
	v_add_u32_e32 v143, 86784, v142
	v_add_u32_e32 v142, 84480, v142
	v_lshlrev_b32_e32 v11, 9, v2
	v_lshl_add_u32 v11, v3, 6, v11
	v_add_u32_e32 v11, 89088, v11
	s_lshl_b32 s69, s8, 6
	s_add_i32 s69, s69, s16
	v_lshl_add_u32 v106, v3, 2, s69
	v_lshlrev_b32_e32 v106, 2, v106
	s_waitcnt lgkmcnt(0)
	global_load_dwordx4 v[12:15], v106, s[12:13]
	global_load_dwordx4 v[16:19], v106, s[12:13] offset:128
	global_load_dwordx4 v[20:23], v106, s[14:15]
	global_load_dwordx4 v[24:27], v106, s[14:15] offset:128
	global_load_dwordx2 v[28:29], v5, s[36:37]
	global_load_dwordx2 v[30:31], v5, s[36:37] offset:64
	global_load_dwordx2 v[32:33], v5, s[38:39]
	global_load_dwordx2 v[34:35], v5, s[38:39] offset:64
	global_load_dwordx2 v[36:37], v5, s[40:41]
	global_load_dwordx2 v[38:39], v5, s[40:41] offset:64
	global_load_dwordx2 v[40:41], v5, s[42:43]
	global_load_dwordx2 v[42:43], v5, s[42:43] offset:64
	global_load_dword v44, v6, s[46:47]
	global_load_dword v45, v9, s[44:45]
	v_add_u32_e32 v5, s54, v5
	v_add_u32_e32 v6, s55, v6
	v_add_u32_e32 v9, s54, v9
	global_load_dwordx2 v[46:47], v5, s[36:37]
	global_load_dwordx2 v[48:49], v5, s[36:37] offset:64
	global_load_dwordx2 v[50:51], v5, s[38:39]
	global_load_dwordx2 v[52:53], v5, s[38:39] offset:64
	global_load_dwordx2 v[54:55], v5, s[40:41]
	global_load_dwordx2 v[56:57], v5, s[40:41] offset:64
	global_load_dwordx2 v[58:59], v5, s[42:43]
	global_load_dwordx2 v[60:61], v5, s[42:43] offset:64
	global_load_dword v62, v6, s[46:47]
	global_load_dword v63, v9, s[44:45]
	v_add_u32_e32 v5, s54, v5
	v_add_u32_e32 v6, s55, v6
	v_add_u32_e32 v9, s54, v9
	s_mov_b32 s6, 0
.Lsc_G_loop:
	s_cmp_ge_u32 s6, 0x100
	s_cbranch_scc1 .Lsc_G_nostage0
	s_cmp_ge_u32 s6, 0xff
	s_cbranch_scc1 .Lsc_G_w0_0
	s_waitcnt vmcnt(10)
	s_branch .Lsc_G_wd_0

.Lsc_G_wd_0:
	v_lshlrev_b32_e32 v106, 16, v36
	v_and_b32_e32 v107, 0xffff0000, v36
	v_mul_f32_e32 v106, 0xbfb8aa3b, v106
	v_mul_f32_e32 v107, 0xbfb8aa3b, v107
	v_exp_f32_e32 v64, v106
	v_exp_f32_e32 v65, v107
	v_lshlrev_b32_e32 v106, 16, v37
	v_and_b32_e32 v107, 0xffff0000, v37
	v_mul_f32_e32 v106, 0xbfb8aa3b, v106
	v_mul_f32_e32 v107, 0xbfb8aa3b, v107
	v_exp_f32_e32 v66, v106
	v_exp_f32_e32 v67, v107
	v_lshlrev_b32_e32 v106, 16, v38
	v_and_b32_e32 v107, 0xffff0000, v38
	v_mul_f32_e32 v106, 0xbfb8aa3b, v106
	v_mul_f32_e32 v107, 0xbfb8aa3b, v107
	v_exp_f32_e32 v68, v106
	v_exp_f32_e32 v69, v107
	v_lshlrev_b32_e32 v106, 16, v39
	v_and_b32_e32 v107, 0xffff0000, v39
	v_mul_f32_e32 v106, 0xbfb8aa3b, v106
	v_mul_f32_e32 v107, 0xbfb8aa3b, v107
	v_exp_f32_e32 v70, v106
	v_exp_f32_e32 v71, v107
	v_lshlrev_b32_e32 v108, 16, v32
	v_and_b32_e32 v109, 0xffff0000, v32
	v_lshlrev_b32_e32 v110, 16, v40
	v_and_b32_e32 v111, 0xffff0000, v40
	v_lshlrev_b32_e32 v96, 16, v28
	v_and_b32_e32 v97, 0xffff0000, v28
	v_pk_add_f32 v[112:113], v[110:111], -1.0 op_sel_hi:[1,0]
	v_pk_mul_f32 v[114:115], v[12:13], v[108:109]
	v_pk_fma_f32 v[112:113], v[20:21], v[112:113], 1.0 op_sel_hi:[1,1,0]
	v_pk_mul_f32 v[88:89], v[44:45], v[114:115] op_sel_hi:[0,1]
	v_pk_mul_f32 v[72:73], v[112:113], v[108:109]
	v_pk_mul_f32 v[80:81], v[88:89], v[110:111]
	v_lshlrev_b32_e32 v108, 16, v33
	v_and_b32_e32 v109, 0xffff0000, v33
	v_lshlrev_b32_e32 v110, 16, v41
	v_and_b32_e32 v111, 0xffff0000, v41
	v_lshlrev_b32_e32 v98, 16, v29
	v_and_b32_e32 v99, 0xffff0000, v29
	v_pk_add_f32 v[112:113], v[110:111], -1.0 op_sel_hi:[1,0]
	v_pk_mul_f32 v[114:115], v[14:15], v[108:109]
	v_pk_fma_f32 v[112:113], v[22:23], v[112:113], 1.0 op_sel_hi:[1,1,0]
	v_pk_mul_f32 v[90:91], v[44:45], v[114:115] op_sel_hi:[0,1]
	v_pk_mul_f32 v[74:75], v[112:113], v[108:109]
	v_pk_mul_f32 v[82:83], v[90:91], v[110:111]
	v_lshlrev_b32_e32 v108, 16, v34
	v_and_b32_e32 v109, 0xffff0000, v34
	v_lshlrev_b32_e32 v110, 16, v42
	v_and_b32_e32 v111, 0xffff0000, v42
	v_lshlrev_b32_e32 v100, 16, v30
	v_and_b32_e32 v101, 0xffff0000, v30
	v_pk_add_f32 v[112:113], v[110:111], -1.0 op_sel_hi:[1,0]
	v_pk_mul_f32 v[114:115], v[16:17], v[108:109]
	v_pk_fma_f32 v[112:113], v[24:25], v[112:113], 1.0 op_sel_hi:[1,1,0]
	v_pk_mul_f32 v[92:93], v[44:45], v[114:115] op_sel_hi:[0,1]
	v_pk_mul_f32 v[76:77], v[112:113], v[108:109]
	v_pk_mul_f32 v[84:85], v[92:93], v[110:111]
	v_lshlrev_b32_e32 v108, 16, v35
	v_and_b32_e32 v109, 0xffff0000, v35
	v_lshlrev_b32_e32 v110, 16, v43
	v_and_b32_e32 v111, 0xffff0000, v43
	v_lshlrev_b32_e32 v102, 16, v31
	v_and_b32_e32 v103, 0xffff0000, v31
	v_pk_add_f32 v[112:113], v[110:111], -1.0 op_sel_hi:[1,0]
	v_pk_mul_f32 v[114:115], v[18:19], v[108:109]
	v_pk_fma_f32 v[112:113], v[26:27], v[112:113], 1.0 op_sel_hi:[1,1,0]
	v_pk_mul_f32 v[94:95], v[44:45], v[114:115] op_sel_hi:[0,1]
	v_pk_mul_f32 v[78:79], v[112:113], v[108:109]
	v_pk_mul_f32 v[86:87], v[94:95], v[110:111]
	v_lshlrev_b32_e32 v104, 16, v45
	v_and_b32_e32 v105, 0xffff0000, v45
	ds_write_b128 v8, v[64:67] offset:0
	ds_write_b128 v8, v[68:71] offset:128
	ds_write_b128 v8, v[72:75] offset:256
	ds_write_b128 v8, v[76:79] offset:384
	ds_write_b128 v8, v[80:83] offset:512
	ds_write_b128 v8, v[84:87] offset:640
	ds_write2_b32 v138, v96, v97 offset0:1 offset1:3
	ds_write2_b32 v139, v88, v89 offset0:0 offset1:2
	ds_write2_b32 v138, v98, v99 offset0:65 offset1:67
	ds_write2_b32 v139, v90, v91 offset0:64 offset1:66
	ds_write2_b32 v138, v100, v101 offset0:33 offset1:35
	ds_write2_b32 v139, v92, v93 offset0:32 offset1:34
	ds_write2_b32 v138, v102, v103 offset0:97 offset1:99
	ds_write2_b32 v139, v94, v95 offset0:96 offset1:98
	ds_write2_b32 v142, v104, v105 offset1:36
	s_cmp_ge_u32 s6, 0xfe
	s_cbranch_scc1 .Lsc_G_nostage0
	global_load_dwordx2 v[28:29], v5, s[36:37]
	global_load_dwordx2 v[30:31], v5, s[36:37] offset:64
	global_load_dwordx2 v[32:33], v5, s[38:39]
	global_load_dwordx2 v[34:35], v5, s[38:39] offset:64
	global_load_dwordx2 v[36:37], v5, s[40:41]
	global_load_dwordx2 v[38:39], v5, s[40:41] offset:64
	global_load_dwordx2 v[40:41], v5, s[42:43]
	global_load_dwordx2 v[42:43], v5, s[42:43] offset:64
	global_load_dword v44, v6, s[46:47]
	global_load_dword v45, v9, s[44:45]
	v_add_u32_e32 v5, s54, v5
	v_add_u32_e32 v6, s55, v6
	v_add_u32_e32 v9, s54, v9
.Lsc_G_nostage0:
	s_cmp_lt_u32 s6, 2
	s_cbranch_scc1 .Lsc_G_noy0
	ds_read_b128 v[120:123], v11 offset:0
	ds_read_b128 v[124:127], v11 offset:16
	ds_read_b128 v[128:131], v11 offset:32
	ds_read_b128 v[132:135], v11 offset:48
	s_waitcnt lgkmcnt(0)
	v_add_f32_e32 v120, v120, v121
	v_add_f32_e32 v122, v122, v123
	v_add_f32_e32 v124, v124, v125
	v_add_f32_e32 v126, v126, v127
	v_add_f32_e32 v120, v120, v122
	v_add_f32_e32 v124, v124, v126
	v_add_f32_e32 v136, v120, v124
	v_add_f32_e32 v128, v128, v129
	v_add_f32_e32 v130, v130, v131
	v_add_f32_e32 v132, v132, v133
	v_add_f32_e32 v134, v134, v135
	v_add_f32_e32 v128, v128, v130
	v_add_f32_e32 v132, v132, v134
	v_add_f32_e32 v137, v128, v132
	global_store_dwordx2 v7, v[136:137], s[48:49]
	v_add_u32_e32 v7, s64, v7
.Lsc_G_noy0:
	s_add_i32 s6, s6, 1
	s_waitcnt lgkmcnt(0)
	s_barrier
	s_cmp_ge_u32 s6, 0x100
	s_cbranch_scc1 .Lsc_G_nostage1
	s_cmp_ge_u32 s6, 0xff
	s_cbranch_scc1 .Lsc_G_w0_1
	s_waitcnt vmcnt(10)
	s_branch .Lsc_G_wd_1

.Lsc_G_wd_1:
	v_lshlrev_b32_e32 v106, 16, v54
	v_and_b32_e32 v107, 0xffff0000, v54
	v_mul_f32_e32 v106, 0xbfb8aa3b, v106
	v_mul_f32_e32 v107, 0xbfb8aa3b, v107
	v_exp_f32_e32 v64, v106
	v_exp_f32_e32 v65, v107
	v_lshlrev_b32_e32 v106, 16, v55
	v_and_b32_e32 v107, 0xffff0000, v55
	v_mul_f32_e32 v106, 0xbfb8aa3b, v106
	v_mul_f32_e32 v107, 0xbfb8aa3b, v107
	v_exp_f32_e32 v66, v106
	v_exp_f32_e32 v67, v107
	v_lshlrev_b32_e32 v106, 16, v56
	v_and_b32_e32 v107, 0xffff0000, v56
	v_mul_f32_e32 v106, 0xbfb8aa3b, v106
	v_mul_f32_e32 v107, 0xbfb8aa3b, v107
	v_exp_f32_e32 v68, v106
	v_exp_f32_e32 v69, v107
	v_lshlrev_b32_e32 v106, 16, v57
	v_and_b32_e32 v107, 0xffff0000, v57
	v_mul_f32_e32 v106, 0xbfb8aa3b, v106
	v_mul_f32_e32 v107, 0xbfb8aa3b, v107
	v_exp_f32_e32 v70, v106
	v_exp_f32_e32 v71, v107
	v_lshlrev_b32_e32 v108, 16, v50
	v_and_b32_e32 v109, 0xffff0000, v50
	v_lshlrev_b32_e32 v110, 16, v58
	v_and_b32_e32 v111, 0xffff0000, v58
	v_lshlrev_b32_e32 v96, 16, v46
	v_and_b32_e32 v97, 0xffff0000, v46
	v_pk_add_f32 v[112:113], v[110:111], -1.0 op_sel_hi:[1,0]
	v_pk_mul_f32 v[114:115], v[12:13], v[108:109]
	v_pk_fma_f32 v[112:113], v[20:21], v[112:113], 1.0 op_sel_hi:[1,1,0]
	v_pk_mul_f32 v[88:89], v[62:63], v[114:115] op_sel_hi:[0,1]
	v_pk_mul_f32 v[72:73], v[112:113], v[108:109]
	v_pk_mul_f32 v[80:81], v[88:89], v[110:111]
	v_lshlrev_b32_e32 v108, 16, v51
	v_and_b32_e32 v109, 0xffff0000, v51
	v_lshlrev_b32_e32 v110, 16, v59
	v_and_b32_e32 v111, 0xffff0000, v59
	v_lshlrev_b32_e32 v98, 16, v47
	v_and_b32_e32 v99, 0xffff0000, v47
	v_pk_add_f32 v[112:113], v[110:111], -1.0 op_sel_hi:[1,0]
	v_pk_mul_f32 v[114:115], v[14:15], v[108:109]
	v_pk_fma_f32 v[112:113], v[22:23], v[112:113], 1.0 op_sel_hi:[1,1,0]
	v_pk_mul_f32 v[90:91], v[62:63], v[114:115] op_sel_hi:[0,1]
	v_pk_mul_f32 v[74:75], v[112:113], v[108:109]
	v_pk_mul_f32 v[82:83], v[90:91], v[110:111]
	v_lshlrev_b32_e32 v108, 16, v52
	v_and_b32_e32 v109, 0xffff0000, v52
	v_lshlrev_b32_e32 v110, 16, v60
	v_and_b32_e32 v111, 0xffff0000, v60
	v_lshlrev_b32_e32 v100, 16, v48
	v_and_b32_e32 v101, 0xffff0000, v48
	v_pk_add_f32 v[112:113], v[110:111], -1.0 op_sel_hi:[1,0]
	v_pk_mul_f32 v[114:115], v[16:17], v[108:109]
	v_pk_fma_f32 v[112:113], v[24:25], v[112:113], 1.0 op_sel_hi:[1,1,0]
	v_pk_mul_f32 v[92:93], v[62:63], v[114:115] op_sel_hi:[0,1]
	v_pk_mul_f32 v[76:77], v[112:113], v[108:109]
	v_pk_mul_f32 v[84:85], v[92:93], v[110:111]
	v_lshlrev_b32_e32 v108, 16, v53
	v_and_b32_e32 v109, 0xffff0000, v53
	v_lshlrev_b32_e32 v110, 16, v61
	v_and_b32_e32 v111, 0xffff0000, v61
	v_lshlrev_b32_e32 v102, 16, v49
	v_and_b32_e32 v103, 0xffff0000, v49
	v_pk_add_f32 v[112:113], v[110:111], -1.0 op_sel_hi:[1,0]
	v_pk_mul_f32 v[114:115], v[18:19], v[108:109]
	v_pk_fma_f32 v[112:113], v[26:27], v[112:113], 1.0 op_sel_hi:[1,1,0]
	v_pk_mul_f32 v[94:95], v[62:63], v[114:115] op_sel_hi:[0,1]
	v_pk_mul_f32 v[78:79], v[112:113], v[108:109]
	v_pk_mul_f32 v[86:87], v[94:95], v[110:111]
	v_lshlrev_b32_e32 v104, 16, v63
	v_and_b32_e32 v105, 0xffff0000, v63
	ds_write_b128 v8, v[64:67] offset:42240
	ds_write_b128 v8, v[68:71] offset:42368
	ds_write_b128 v8, v[72:75] offset:42496
	ds_write_b128 v8, v[76:79] offset:42624
	ds_write_b128 v8, v[80:83] offset:42752
	ds_write_b128 v8, v[84:87] offset:42880
	ds_write2_b32 v140, v96, v97 offset0:1 offset1:3
	ds_write2_b32 v141, v88, v89 offset0:0 offset1:2
	ds_write2_b32 v140, v98, v99 offset0:65 offset1:67
	ds_write2_b32 v141, v90, v91 offset0:64 offset1:66
	ds_write2_b32 v140, v100, v101 offset0:33 offset1:35
	ds_write2_b32 v141, v92, v93 offset0:32 offset1:34
	ds_write2_b32 v140, v102, v103 offset0:97 offset1:99
	ds_write2_b32 v141, v94, v95 offset0:96 offset1:98
	ds_write2_b32 v143, v104, v105 offset1:36
	s_cmp_ge_u32 s6, 0xfe
	s_cbranch_scc1 .Lsc_G_nostage1
	global_load_dwordx2 v[46:47], v5, s[36:37]
	global_load_dwordx2 v[48:49], v5, s[36:37] offset:64
	global_load_dwordx2 v[50:51], v5, s[38:39]
	global_load_dwordx2 v[52:53], v5, s[38:39] offset:64
	global_load_dwordx2 v[54:55], v5, s[40:41]
	global_load_dwordx2 v[56:57], v5, s[40:41] offset:64
	global_load_dwordx2 v[58:59], v5, s[42:43]
	global_load_dwordx2 v[60:61], v5, s[42:43] offset:64
	global_load_dword v62, v6, s[46:47]
	global_load_dword v63, v9, s[44:45]
	v_add_u32_e32 v5, s54, v5
	v_add_u32_e32 v6, s55, v6
	v_add_u32_e32 v9, s54, v9
.Lsc_G_nostage1:
	s_cmp_lt_u32 s6, 2
	s_cbranch_scc1 .Lsc_G_noy1
	ds_read_b128 v[120:123], v11 offset:16384
	ds_read_b128 v[124:127], v11 offset:16400
	ds_read_b128 v[128:131], v11 offset:16416
	ds_read_b128 v[132:135], v11 offset:16432
	s_waitcnt lgkmcnt(0)
	v_add_f32_e32 v120, v120, v121
	v_add_f32_e32 v122, v122, v123
	v_add_f32_e32 v124, v124, v125
	v_add_f32_e32 v126, v126, v127
	v_add_f32_e32 v120, v120, v122
	v_add_f32_e32 v124, v124, v126
	v_add_f32_e32 v136, v120, v124
	v_add_f32_e32 v128, v128, v129
	v_add_f32_e32 v130, v130, v131
	v_add_f32_e32 v132, v132, v133
	v_add_f32_e32 v134, v134, v135
	v_add_f32_e32 v128, v128, v130
	v_add_f32_e32 v132, v132, v134
	v_add_f32_e32 v137, v128, v132
	global_store_dwordx2 v7, v[136:137], s[48:49]
	v_add_u32_e32 v7, s64, v7
.Lsc_G_noy1:
	s_add_i32 s6, s6, 1
	s_waitcnt lgkmcnt(0)
	s_barrier
	s_cmp_lg_u32 s6, 0x102
	s_cbranch_scc1 .Lsc_G_loop
.Lsc_item_end:
	s_add_i32 s4, s4, s3
	s_cmpk_gt_i32 s4, 0xff
	s_waitcnt lgkmcnt(0)
	s_barrier
	s_cbranch_scc0 .Lsc_item
